# GEMM K-loops: one static s_setprio 1 for waves 4..7 over the K loop
# baseline (speedup 1.0000x reference)
; template <class Epi>
; DI void gemm_tile256(const u16* __restrict__ Ag, long lda, const u16* __restrict__ Bg, long ldb, int nk, char* shm, Epi&& epi) {
;   const int tid = RTID, wid = tid >> 6, lane = tid & 63, wr = wid >> 2, wc = wid & 3, fr = lane & 15, fq = lane >> 4;
;   f32x4 acc[8][4];
; #pragma unroll
;   for (int m = 0; m < 8; ++m)
; #pragma unroll
;     for (int n = 0; n < 4; ++n) acc[m][n] = f32x4{0.f, 0.f, 0.f, 0.f};
;   const int q0 = tid, q1 = 512 + tid;
;   const int r0 = q0 >> 2, r1 = q1 >> 2, c0 = (q0 & 3) ^ ((r0 >> 2) & 3), c1 = (q1 & 3) ^ ((r1 >> 2) & 3);
;   const u16* a0 = Ag + (long)r0 * lda + c0 * 8; const u16* a1 = Ag + (long)r1 * lda + c1 * 8;
;   const u16* b0 = Bg + (long)r0 * ldb + c0 * 8; const u16* b1 = Bg + (long)r1 * ldb + c1 * 8;
;   auto stage = [&](int j) {
;     char* SA = shm + (j & 3) * 32768; char* SB = SA + 16384;
;     __builtin_amdgcn_global_load_lds((const unsigned*)(a0 + j * 32), (__attribute__((address_space(3))) unsigned*)(SA + q0 * 16), 16, 0, 0);
;     __builtin_amdgcn_global_load_lds((const unsigned*)(a1 + j * 32), (__attribute__((address_space(3))) unsigned*)(SA + q1 * 16), 16, 0, 0);
;     __builtin_amdgcn_global_load_lds((const unsigned*)(b0 + j * 32), (__attribute__((address_space(3))) unsigned*)(SB + q0 * 16), 16, 0, 0);
;     __builtin_amdgcn_global_load_lds((const unsigned*)(b1 + j * 32), (__attribute__((address_space(3))) unsigned*)(SB + q1 * 16), 16, 0, 0);
;   };
;   __syncthreads();
;   stage(0);
;   if (nk > 1) stage(1);
;   if (nk > 2) stage(2);
; DI void phase1(const Params& P, char* smem) {
;     ...
;   for (int q = RBLK >> 3; q < 128; q += RGRID >> 3) {
;     const int brow = q * 256, bcol = (RBLK & 7) * 256;
;     gemm_tile256(xb + (long)brow * 1024, 1024, WinT + (long)bcol * 1024, 1024, 32, smem, [&](int row, int col0, f32x4 v) {
.LBB0_107:
	v_lshl_add_u64 v[176:177], v[138:139], 0, 64
	v_lshl_add_u64 v[178:179], v[140:141], 0, 64
	v_lshl_add_u64 v[180:181], v[138:139], 0, s[0:1]
	v_lshl_add_u64 v[182:183], v[140:141], 0, s[0:1]
	s_lshl_b32 s30, s27, 8
	s_ashr_i32 s29, s28, 31
	s_ashr_i32 s31, s30, 31
	s_lshl_b64 s[6:7], s[28:29], 11
	s_lshl_b64 s[4:5], s[30:31], 11
	s_add_u32 s4, s54, s4
	s_addc_u32 s5, s55, s5
	v_add_u32_e32 v6, 0, v209
	v_lshl_add_u64 v[0:1], s[4:5], 0, v[132:133]
	v_lshl_add_u64 v[2:3], s[4:5], 0, v[136:137]
	v_readfirstlane_b32 s4, v6
	v_add_u32_e32 v7, 0, v131
	v_lshl_add_u64 v[0:1], v[0:1], 0, v[134:135]
	s_mov_b32 m0, s4
	v_readfirstlane_b32 s4, v7
	v_add_u32_e32 v4, 0x4000, v6
	v_lshl_add_u64 v[2:3], v[2:3], 0, v[134:135]
	s_barrier
	global_load_lds_dwordx4 v[0:1], off
	s_mov_b32 m0, s4
	v_readfirstlane_b32 s4, v4
	v_add_u32_e32 v4, 0x4000, v7
	global_load_lds_dwordx4 v[2:3], off
	s_mov_b32 m0, s4
	v_readfirstlane_b32 s4, v4
	v_add_u32_e32 v8, 0x8000, v6
	global_load_lds_dwordx4 v[138:139], off
	s_mov_b32 m0, s4
	v_readfirstlane_b32 s4, v8
	v_add_u32_e32 v8, 0x8000, v7
	global_load_lds_dwordx4 v[140:141], off
	v_lshl_add_u64 v[4:5], v[0:1], 0, 64
	s_mov_b32 m0, s4
	v_readfirstlane_b32 s4, v8
	global_load_lds_dwordx4 v[4:5], off
	v_lshl_add_u64 v[4:5], v[2:3], 0, 64
	s_mov_b32 m0, s4
	v_lshl_add_u64 v[0:1], v[0:1], 0, s[0:1]
	global_load_lds_dwordx4 v[4:5], off
	v_add_u32_e32 v4, 0xc000, v6
	s_mov_b32 s8, 0x18000
	v_readfirstlane_b32 s4, v4
	v_add_u32_e32 v4, 0xc000, v7
	s_mov_b32 m0, s4
	v_readfirstlane_b32 s4, v4
	v_add_u32_e32 v4, s2, v209
	global_load_lds_dwordx4 v[176:177], off
	s_mov_b32 m0, s4
	v_readfirstlane_b32 s4, v4
	global_load_lds_dwordx4 v[178:179], off
	s_mov_b32 m0, s4
	v_mov_b32_e32 v4, 0
	global_load_lds_dwordx4 v[0:1], off
	v_lshl_add_u64 v[0:1], v[2:3], 0, s[0:1]
	v_add_u32_e32 v2, s2, v131
	v_mov_b32_e32 v3, v135
	v_readfirstlane_b32 s4, v2
	s_mov_b32 m0, s4
	v_mov_b32_e32 v2, v135
	global_load_lds_dwordx4 v[0:1], off
	v_add_u32_e32 v0, s15, v209
	v_mov_b32_e32 v1, v135
	v_readfirstlane_b32 s4, v0
	v_add_u32_e32 v0, s15, v131
	s_mov_b32 m0, s4
	v_readfirstlane_b32 s4, v0
	global_load_lds_dwordx4 v[180:181], off
	s_mov_b32 m0, s4
	s_mov_b64 s[4:5], 0
	global_load_lds_dwordx4 v[182:183], off
	v_mov_b32_e32 v0, 0
	v_mov_b32_e32 v5, v135
	v_mov_b32_e32 v6, v135
	v_mov_b32_e32 v7, v135
	v_mov_b32_e32 v8, 0
	v_mov_b32_e32 v9, v135
	v_mov_b32_e32 v10, v135
	v_mov_b32_e32 v11, v135
	v_mov_b32_e32 v12, 0
	v_mov_b32_e32 v13, v135
	v_mov_b32_e32 v14, v135
	v_mov_b32_e32 v15, v135
	v_mov_b32_e32 v16, 0
	v_mov_b32_e32 v17, v135
	v_mov_b32_e32 v18, v135
	v_mov_b32_e32 v19, v135
	v_mov_b32_e32 v20, 0
	v_mov_b32_e32 v21, v135
	v_mov_b32_e32 v22, v135
	v_mov_b32_e32 v23, v135
	v_mov_b32_e32 v24, 0
	v_mov_b32_e32 v25, v135
	v_mov_b32_e32 v26, v135
	v_mov_b32_e32 v27, v135
	v_mov_b32_e32 v28, 0
	v_mov_b32_e32 v29, v135
	v_mov_b32_e32 v30, v135
	v_mov_b32_e32 v31, v135
	v_mov_b32_e32 v32, 0
	v_mov_b32_e32 v33, v135
	v_mov_b32_e32 v34, v135
	v_mov_b32_e32 v35, v135
	v_mov_b32_e32 v36, 0
	v_mov_b32_e32 v37, v135
	v_mov_b32_e32 v38, v135
	v_mov_b32_e32 v39, v135
	v_mov_b32_e32 v40, 0
	v_mov_b32_e32 v41, v135
	v_mov_b32_e32 v42, v135
	v_mov_b32_e32 v43, v135
	v_mov_b32_e32 v44, 0
	v_mov_b32_e32 v45, v135
	v_mov_b32_e32 v46, v135
	v_mov_b32_e32 v47, v135
	v_mov_b32_e32 v48, 0
	v_mov_b32_e32 v49, v135
	v_mov_b32_e32 v50, v135
	v_mov_b32_e32 v51, v135
	v_mov_b32_e32 v52, 0
	v_mov_b32_e32 v53, v135
	v_mov_b32_e32 v54, v135
	v_mov_b32_e32 v55, v135
	v_mov_b32_e32 v56, 0
	v_mov_b32_e32 v57, v135
	v_mov_b32_e32 v58, v135
	v_mov_b32_e32 v59, v135
	v_mov_b32_e32 v60, 0
	v_mov_b32_e32 v61, v135
	v_mov_b32_e32 v62, v135
	v_mov_b32_e32 v63, v135
	v_mov_b32_e32 v64, 0
	v_mov_b32_e32 v65, v135
	v_mov_b32_e32 v66, v135
	v_mov_b32_e32 v67, v135
	v_mov_b32_e32 v68, 0
	v_mov_b32_e32 v69, v135
	v_mov_b32_e32 v70, v135
	v_mov_b32_e32 v71, v135
	v_mov_b32_e32 v72, 0
	v_mov_b32_e32 v73, v135
	v_mov_b32_e32 v74, v135
	v_mov_b32_e32 v75, v135
	v_mov_b32_e32 v76, 0
	v_mov_b32_e32 v77, v135
	v_mov_b32_e32 v78, v135
	v_mov_b32_e32 v79, v135
	v_mov_b32_e32 v80, 0
	v_mov_b32_e32 v81, v135
	v_mov_b32_e32 v82, v135
	v_mov_b32_e32 v83, v135
	v_mov_b32_e32 v84, 0
	v_mov_b32_e32 v85, v135
	v_mov_b32_e32 v86, v135
	v_mov_b32_e32 v87, v135
	v_mov_b32_e32 v88, 0
	v_mov_b32_e32 v89, v135
	v_mov_b32_e32 v90, v135
	v_mov_b32_e32 v91, v135
	v_mov_b32_e32 v92, 0
	v_mov_b32_e32 v93, v135
	v_mov_b32_e32 v94, v135
	v_mov_b32_e32 v95, v135
	v_mov_b32_e32 v96, 0
	v_mov_b32_e32 v97, v135
	v_mov_b32_e32 v98, v135
	v_mov_b32_e32 v99, v135
	v_mov_b32_e32 v100, 0
	v_mov_b32_e32 v101, v135
	v_mov_b32_e32 v102, v135
	v_mov_b32_e32 v103, v135
	v_mov_b32_e32 v104, 0
	v_mov_b32_e32 v105, v135
	v_mov_b32_e32 v106, v135
	v_mov_b32_e32 v107, v135
	v_mov_b32_e32 v108, 0
	v_mov_b32_e32 v109, v135
	v_mov_b32_e32 v110, v135
	v_mov_b32_e32 v111, v135
	v_mov_b32_e32 v112, 0
	v_mov_b32_e32 v113, v135
	v_mov_b32_e32 v114, v135
	v_mov_b32_e32 v115, v135
	v_mov_b32_e32 v116, 0
	v_mov_b32_e32 v117, v135
	v_mov_b32_e32 v118, v135
	v_mov_b32_e32 v119, v135
	v_mov_b32_e32 v120, 0
	v_mov_b32_e32 v121, v135
	v_mov_b32_e32 v122, v135
	v_mov_b32_e32 v123, v135
	v_mov_b32_e32 v124, 0
	v_mov_b32_e32 v125, v135
	v_mov_b32_e32 v126, v135
	v_mov_b32_e32 v127, v135
	v_lshl_add_u64 v[184:185], v[168:169], 0, s[6:7]
	v_lshl_add_u64 v[186:187], v[170:171], 0, s[6:7]
	v_readfirstlane_b32 s7, v209
	s_mov_b32 s8, 0
	s_mov_b64 s[4:5], 0
	s_cmpk_lt_u32 s7, 0x1000
	s_cbranch_scc1 .Lgemm_p1_np
	s_setprio 1
; template <class Epi>
; DI void gemm_tile256(const u16* __restrict__ Ag, long lda, const u16* __restrict__ Bg, long ldb, int nk, char* shm, Epi&& epi) {
;     ...
;   for (int i = 0; i < nk; ++i) {
;     if (i + 2 < nk) asm volatile("s_waitcnt vmcnt(8)" ::: "memory");
;     else if (i + 1 < nk) asm volatile("s_waitcnt vmcnt(4)" ::: "memory");
;     else asm volatile("s_waitcnt vmcnt(0)" ::: "memory");
;     __builtin_amdgcn_s_barrier();
;     const char* SA = shm + (i & 3) * 32768; const char* SB = SA + 16384;
;     bf16x8 At[8], Bt[4];
; #pragma unroll
;     for (int n = 0; n < 4; ++n) { const int rb = wc * 64 + n * 16 + fr; Bt[n] = *reinterpret_cast<const bf16x8*>(SB + rb * 64 + ((fq ^ ((rb >> 2) & 3)) * 16)); }
; #pragma unroll
;     for (int m = 0; m < 8; ++m) { const int ra = wr * 128 + m * 16 + fr; At[m] = *reinterpret_cast<const bf16x8*>(SA + ra * 64 + ((fq ^ ((ra >> 2) & 3)) * 16)); }
;     if (i + 3 < nk) stage(i + 3);
; #pragma unroll
;     for (int m = 0; m < 8; ++m)
; #pragma unroll
;       for (int n = 0; n < 4; ++n) acc[m][n] = __builtin_amdgcn_mfma_f32_16x16x32_bf16(Bt[n], At[m], acc[m][n], 0, 0, 0);
;   }
.Lgemm_p1_np:
	s_and_b64 vcc, exec, s[24:25]
	s_cbranch_vccz .Lgemm_p1_n
	s_waitcnt vmcnt(8)
	s_barrier
	v_add3_u32 v252, v205, v147, s8
	v_add3_u32 v215, v205, v151, s8
	s_nop 0
	ds_read_b128 v[216:219], v252 offset:16384
	ds_read_b128 v[220:223], v252 offset:17408
	ds_read_b128 v[232:235], v252 offset:18432
	ds_read_b128 v[236:239], v252 offset:19456
	ds_read_b128 v[224:227], v215
	ds_read_b128 v[228:231], v215 offset:1024
.Lgemm_p1_kloopv:
	s_add_i32 s6, s8, 0x18000
	s_and_b32 s6, s6, 0x18000
	s_add_i32 s9, s6, s7
	ds_read_b128 v[180:183], v215 offset:2048
	ds_read_b128 v[210:213], v215 offset:3072
	s_waitcnt lgkmcnt(2)
	v_mfma_f32_16x16x32_bf16 v[124:127], v[224:227], v[216:219], v[124:127]
	v_lshl_add_u64 v[206:207], v[184:185], 0, s[4:5]
	v_mfma_f32_16x16x32_bf16 v[120:123], v[224:227], v[220:223], v[120:123]
	s_mov_b32 m0, s9
	v_mfma_f32_16x16x32_bf16 v[116:119], v[224:227], v[232:235], v[116:119]
	s_add_i32 s9, s9, 0x2000
	v_mfma_f32_16x16x32_bf16 v[112:115], v[224:227], v[236:239], v[112:115]
	global_load_lds_dwordx4 v[206:207], off
	v_mfma_f32_16x16x32_bf16 v[108:111], v[228:231], v[216:219], v[108:111]
	v_mfma_f32_16x16x32_bf16 v[104:107], v[228:231], v[220:223], v[104:107]
	v_mfma_f32_16x16x32_bf16 v[100:103], v[228:231], v[232:235], v[100:103]
	v_mfma_f32_16x16x32_bf16 v[96:99], v[228:231], v[236:239], v[96:99]
	ds_read_b128 v[224:227], v215 offset:4096
	ds_read_b128 v[228:231], v215 offset:5120
	s_waitcnt lgkmcnt(2)
	v_mfma_f32_16x16x32_bf16 v[92:95], v[180:183], v[216:219], v[92:95]
	v_lshl_add_u64 v[206:207], v[186:187], 0, s[4:5]
	v_mfma_f32_16x16x32_bf16 v[88:91], v[180:183], v[220:223], v[88:91]
	s_mov_b32 m0, s9
	v_mfma_f32_16x16x32_bf16 v[84:87], v[180:183], v[232:235], v[84:87]
	s_add_i32 s9, s9, 0x2000
	v_mfma_f32_16x16x32_bf16 v[80:83], v[180:183], v[236:239], v[80:83]
	global_load_lds_dwordx4 v[206:207], off
	v_mfma_f32_16x16x32_bf16 v[76:79], v[210:213], v[216:219], v[76:79]
	v_mfma_f32_16x16x32_bf16 v[72:75], v[210:213], v[220:223], v[72:75]
	v_mfma_f32_16x16x32_bf16 v[68:71], v[210:213], v[232:235], v[68:71]
	v_mfma_f32_16x16x32_bf16 v[64:67], v[210:213], v[236:239], v[64:67]
	ds_read_b128 v[180:183], v215 offset:6144
	ds_read_b128 v[210:213], v215 offset:7168
	s_waitcnt lgkmcnt(2)
	v_mfma_f32_16x16x32_bf16 v[60:63], v[224:227], v[216:219], v[60:63]
	v_lshl_add_u64 v[206:207], v[172:173], 0, s[4:5]
	v_mfma_f32_16x16x32_bf16 v[56:59], v[224:227], v[220:223], v[56:59]
	s_mov_b32 m0, s9
	v_mfma_f32_16x16x32_bf16 v[52:55], v[224:227], v[232:235], v[52:55]
	s_add_i32 s9, s9, 0x2000
	v_mfma_f32_16x16x32_bf16 v[48:51], v[224:227], v[236:239], v[48:51]
	global_load_lds_dwordx4 v[206:207], off
	v_mfma_f32_16x16x32_bf16 v[44:47], v[228:231], v[216:219], v[44:47]
	v_mfma_f32_16x16x32_bf16 v[40:43], v[228:231], v[220:223], v[40:43]
	v_mfma_f32_16x16x32_bf16 v[36:39], v[228:231], v[232:235], v[36:39]
	v_mfma_f32_16x16x32_bf16 v[32:35], v[228:231], v[236:239], v[32:35]
	s_add_i32 s8, s8, 0x8000
	s_and_b32 s8, s8, 0x18000
	s_waitcnt vmcnt(7) lgkmcnt(0)
	s_barrier
	v_add3_u32 v252, v205, v147, s8
	v_add3_u32 v215, v205, v151, s8
	s_nop 0
	ds_read_b128 v[240:243], v252 offset:16384
	ds_read_b128 v[244:247], v252 offset:17408
	ds_read_b128 v[248:251], v252 offset:18432
	ds_read_b128 v[176:179], v252 offset:19456
	ds_read_b128 v[224:227], v215
	ds_read_b128 v[228:231], v215 offset:1024
	v_mfma_f32_16x16x32_bf16 v[28:31], v[180:183], v[216:219], v[28:31]
	v_lshl_add_u64 v[206:207], v[174:175], 0, s[4:5]
	v_mfma_f32_16x16x32_bf16 v[24:27], v[180:183], v[220:223], v[24:27]
	s_mov_b32 m0, s9
	v_mfma_f32_16x16x32_bf16 v[20:23], v[180:183], v[232:235], v[20:23]
	s_add_i32 s9, s9, 0x2000
	v_mfma_f32_16x16x32_bf16 v[16:19], v[180:183], v[236:239], v[16:19]
	global_load_lds_dwordx4 v[206:207], off
	v_mfma_f32_16x16x32_bf16 v[12:15], v[210:213], v[216:219], v[12:15]
	s_add_u32 s4, s4, 64
	v_mfma_f32_16x16x32_bf16 v[8:11], v[210:213], v[220:223], v[8:11]
	s_addc_u32 s5, s5, 0
	v_mfma_f32_16x16x32_bf16 v[4:7], v[210:213], v[232:235], v[4:7]
	v_mfma_f32_16x16x32_bf16 v[0:3], v[210:213], v[236:239], v[0:3]
	s_add_i32 s6, s8, 0x18000
	s_and_b32 s6, s6, 0x18000
	s_add_i32 s9, s6, s7
	ds_read_b128 v[180:183], v215 offset:2048
	ds_read_b128 v[210:213], v215 offset:3072
	s_waitcnt lgkmcnt(2)
	v_mfma_f32_16x16x32_bf16 v[124:127], v[224:227], v[240:243], v[124:127]
	v_lshl_add_u64 v[206:207], v[184:185], 0, s[4:5]
	v_mfma_f32_16x16x32_bf16 v[120:123], v[224:227], v[244:247], v[120:123]
	s_mov_b32 m0, s9
	v_mfma_f32_16x16x32_bf16 v[116:119], v[224:227], v[248:251], v[116:119]
	s_add_i32 s9, s9, 0x2000
	v_mfma_f32_16x16x32_bf16 v[112:115], v[224:227], v[176:179], v[112:115]
	global_load_lds_dwordx4 v[206:207], off
	v_mfma_f32_16x16x32_bf16 v[108:111], v[228:231], v[240:243], v[108:111]
	v_mfma_f32_16x16x32_bf16 v[104:107], v[228:231], v[244:247], v[104:107]
	v_mfma_f32_16x16x32_bf16 v[100:103], v[228:231], v[248:251], v[100:103]
	v_mfma_f32_16x16x32_bf16 v[96:99], v[228:231], v[176:179], v[96:99]
	ds_read_b128 v[224:227], v215 offset:4096
	ds_read_b128 v[228:231], v215 offset:5120
	s_waitcnt lgkmcnt(2)
	v_mfma_f32_16x16x32_bf16 v[92:95], v[180:183], v[240:243], v[92:95]
	v_lshl_add_u64 v[206:207], v[186:187], 0, s[4:5]
	v_mfma_f32_16x16x32_bf16 v[88:91], v[180:183], v[244:247], v[88:91]
	s_mov_b32 m0, s9
	v_mfma_f32_16x16x32_bf16 v[84:87], v[180:183], v[248:251], v[84:87]
	s_add_i32 s9, s9, 0x2000
	v_mfma_f32_16x16x32_bf16 v[80:83], v[180:183], v[176:179], v[80:83]
	global_load_lds_dwordx4 v[206:207], off
	v_mfma_f32_16x16x32_bf16 v[76:79], v[210:213], v[240:243], v[76:79]
	v_mfma_f32_16x16x32_bf16 v[72:75], v[210:213], v[244:247], v[72:75]
	v_mfma_f32_16x16x32_bf16 v[68:71], v[210:213], v[248:251], v[68:71]
	v_mfma_f32_16x16x32_bf16 v[64:67], v[210:213], v[176:179], v[64:67]
	ds_read_b128 v[180:183], v215 offset:6144
	ds_read_b128 v[210:213], v215 offset:7168
	s_waitcnt lgkmcnt(2)
	v_mfma_f32_16x16x32_bf16 v[60:63], v[224:227], v[240:243], v[60:63]
	v_lshl_add_u64 v[206:207], v[172:173], 0, s[4:5]
	v_mfma_f32_16x16x32_bf16 v[56:59], v[224:227], v[244:247], v[56:59]
	s_mov_b32 m0, s9
	v_mfma_f32_16x16x32_bf16 v[52:55], v[224:227], v[248:251], v[52:55]
	s_add_i32 s9, s9, 0x2000
	v_mfma_f32_16x16x32_bf16 v[48:51], v[224:227], v[176:179], v[48:51]
	global_load_lds_dwordx4 v[206:207], off
	v_mfma_f32_16x16x32_bf16 v[44:47], v[228:231], v[240:243], v[44:47]
	v_mfma_f32_16x16x32_bf16 v[40:43], v[228:231], v[244:247], v[40:43]
	v_mfma_f32_16x16x32_bf16 v[36:39], v[228:231], v[248:251], v[36:39]
	v_mfma_f32_16x16x32_bf16 v[32:35], v[228:231], v[176:179], v[32:35]
	s_add_i32 s8, s8, 0x8000
	s_and_b32 s8, s8, 0x18000
	s_waitcnt vmcnt(7) lgkmcnt(0)
	s_barrier
; template <class Epi>
; DI void gemm_tile256(const u16* __restrict__ Ag, long lda, const u16* __restrict__ Bg, long ldb, int nk, char* shm, Epi&& epi) {
;     ...
;   for (int i = 0; i < nk; ++i) {
;     if (i + 2 < nk) asm volatile("s_waitcnt vmcnt(8)" ::: "memory");
;     else if (i + 1 < nk) asm volatile("s_waitcnt vmcnt(4)" ::: "memory");
;     else asm volatile("s_waitcnt vmcnt(0)" ::: "memory");
;     __builtin_amdgcn_s_barrier();
;     const char* SA = shm + (i & 3) * 32768; const char* SB = SA + 16384;
;     bf16x8 At[8], Bt[4];
; #pragma unroll
;     for (int n = 0; n < 4; ++n) { const int rb = wc * 64 + n * 16 + fr; Bt[n] = *reinterpret_cast<const bf16x8*>(SB + rb * 64 + ((fq ^ ((rb >> 2) & 3)) * 16)); }
; #pragma unroll
;     for (int m = 0; m < 8; ++m) { const int ra = wr * 128 + m * 16 + fr; At[m] = *reinterpret_cast<const bf16x8*>(SA + ra * 64 + ((fq ^ ((ra >> 2) & 3)) * 16)); }
;     if (i + 3 < nk) stage(i + 3);
; #pragma unroll
;     for (int m = 0; m < 8; ++m)
; #pragma unroll
;       for (int n = 0; n < 4; ++n) acc[m][n] = __builtin_amdgcn_mfma_f32_16x16x32_bf16(Bt[n], At[m], acc[m][n], 0, 0, 0);
;   }
	v_add3_u32 v252, v205, v147, s8
	v_add3_u32 v215, v205, v151, s8
	s_nop 0
	ds_read_b128 v[216:219], v252 offset:16384
	ds_read_b128 v[220:223], v252 offset:17408
	ds_read_b128 v[232:235], v252 offset:18432
	ds_read_b128 v[236:239], v252 offset:19456
	ds_read_b128 v[224:227], v215
	ds_read_b128 v[228:231], v215 offset:1024
	v_mfma_f32_16x16x32_bf16 v[28:31], v[180:183], v[240:243], v[28:31]
	v_lshl_add_u64 v[206:207], v[174:175], 0, s[4:5]
	v_mfma_f32_16x16x32_bf16 v[24:27], v[180:183], v[244:247], v[24:27]
	s_mov_b32 m0, s9
	v_mfma_f32_16x16x32_bf16 v[20:23], v[180:183], v[248:251], v[20:23]
	s_add_i32 s9, s9, 0x2000
	v_mfma_f32_16x16x32_bf16 v[16:19], v[180:183], v[176:179], v[16:19]
	global_load_lds_dwordx4 v[206:207], off
	v_mfma_f32_16x16x32_bf16 v[12:15], v[210:213], v[240:243], v[12:15]
	s_add_u32 s4, s4, 64
	v_mfma_f32_16x16x32_bf16 v[8:11], v[210:213], v[244:247], v[8:11]
	s_addc_u32 s5, s5, 0
	v_mfma_f32_16x16x32_bf16 v[4:7], v[210:213], v[248:251], v[4:7]
	v_mfma_f32_16x16x32_bf16 v[0:3], v[210:213], v[176:179], v[0:3]
	s_cmpk_lg_i32 s4, 0x700
	s_cbranch_scc1 .Lgemm_p1_kloopv
	s_add_i32 s6, s8, 0x18000
	s_and_b32 s6, s6, 0x18000
	s_add_i32 s9, s6, s7
	ds_read_b128 v[180:183], v215 offset:2048
	ds_read_b128 v[210:213], v215 offset:3072
	s_waitcnt lgkmcnt(2)
	v_mfma_f32_16x16x32_bf16 v[124:127], v[224:227], v[216:219], v[124:127]
	v_lshl_add_u64 v[206:207], v[184:185], 0, s[4:5]
	v_mfma_f32_16x16x32_bf16 v[120:123], v[224:227], v[220:223], v[120:123]
	s_mov_b32 m0, s9
	v_mfma_f32_16x16x32_bf16 v[116:119], v[224:227], v[232:235], v[116:119]
	s_add_i32 s9, s9, 0x2000
	v_mfma_f32_16x16x32_bf16 v[112:115], v[224:227], v[236:239], v[112:115]
	global_load_lds_dwordx4 v[206:207], off
	v_mfma_f32_16x16x32_bf16 v[108:111], v[228:231], v[216:219], v[108:111]
	v_mfma_f32_16x16x32_bf16 v[104:107], v[228:231], v[220:223], v[104:107]
	v_mfma_f32_16x16x32_bf16 v[100:103], v[228:231], v[232:235], v[100:103]
	v_mfma_f32_16x16x32_bf16 v[96:99], v[228:231], v[236:239], v[96:99]
	ds_read_b128 v[224:227], v215 offset:4096
	ds_read_b128 v[228:231], v215 offset:5120
	s_waitcnt lgkmcnt(2)
	v_mfma_f32_16x16x32_bf16 v[92:95], v[180:183], v[216:219], v[92:95]
	v_lshl_add_u64 v[206:207], v[186:187], 0, s[4:5]
	v_mfma_f32_16x16x32_bf16 v[88:91], v[180:183], v[220:223], v[88:91]
	s_mov_b32 m0, s9
	v_mfma_f32_16x16x32_bf16 v[84:87], v[180:183], v[232:235], v[84:87]
	s_add_i32 s9, s9, 0x2000
	v_mfma_f32_16x16x32_bf16 v[80:83], v[180:183], v[236:239], v[80:83]
	global_load_lds_dwordx4 v[206:207], off
	v_mfma_f32_16x16x32_bf16 v[76:79], v[210:213], v[216:219], v[76:79]
	v_mfma_f32_16x16x32_bf16 v[72:75], v[210:213], v[220:223], v[72:75]
	v_mfma_f32_16x16x32_bf16 v[68:71], v[210:213], v[232:235], v[68:71]
	v_mfma_f32_16x16x32_bf16 v[64:67], v[210:213], v[236:239], v[64:67]
	ds_read_b128 v[180:183], v215 offset:6144
	ds_read_b128 v[210:213], v215 offset:7168
	s_waitcnt lgkmcnt(2)
	v_mfma_f32_16x16x32_bf16 v[60:63], v[224:227], v[216:219], v[60:63]
	v_lshl_add_u64 v[206:207], v[172:173], 0, s[4:5]
	v_mfma_f32_16x16x32_bf16 v[56:59], v[224:227], v[220:223], v[56:59]
	s_mov_b32 m0, s9
	v_mfma_f32_16x16x32_bf16 v[52:55], v[224:227], v[232:235], v[52:55]
	s_add_i32 s9, s9, 0x2000
	v_mfma_f32_16x16x32_bf16 v[48:51], v[224:227], v[236:239], v[48:51]
	global_load_lds_dwordx4 v[206:207], off
	v_mfma_f32_16x16x32_bf16 v[44:47], v[228:231], v[216:219], v[44:47]
	v_mfma_f32_16x16x32_bf16 v[40:43], v[228:231], v[220:223], v[40:43]
	v_mfma_f32_16x16x32_bf16 v[36:39], v[228:231], v[232:235], v[36:39]
	v_mfma_f32_16x16x32_bf16 v[32:35], v[228:231], v[236:239], v[32:35]
	s_add_i32 s8, s8, 0x8000
	s_and_b32 s8, s8, 0x18000
	s_waitcnt vmcnt(7) lgkmcnt(0)
	s_barrier
	v_add3_u32 v252, v205, v147, s8
	v_add3_u32 v215, v205, v151, s8
	s_nop 0
	ds_read_b128 v[240:243], v252 offset:16384
	ds_read_b128 v[244:247], v252 offset:17408
	ds_read_b128 v[248:251], v252 offset:18432
	ds_read_b128 v[176:179], v252 offset:19456
	ds_read_b128 v[224:227], v215
	ds_read_b128 v[228:231], v215 offset:1024
	v_mfma_f32_16x16x32_bf16 v[28:31], v[180:183], v[216:219], v[28:31]
	v_lshl_add_u64 v[206:207], v[174:175], 0, s[4:5]
	v_mfma_f32_16x16x32_bf16 v[24:27], v[180:183], v[220:223], v[24:27]
	s_mov_b32 m0, s9
	v_mfma_f32_16x16x32_bf16 v[20:23], v[180:183], v[232:235], v[20:23]
	s_add_i32 s9, s9, 0x2000
	v_mfma_f32_16x16x32_bf16 v[16:19], v[180:183], v[236:239], v[16:19]
	global_load_lds_dwordx4 v[206:207], off
	v_mfma_f32_16x16x32_bf16 v[12:15], v[210:213], v[216:219], v[12:15]
	s_add_u32 s4, s4, 64
	v_mfma_f32_16x16x32_bf16 v[8:11], v[210:213], v[220:223], v[8:11]
	s_addc_u32 s5, s5, 0
	v_mfma_f32_16x16x32_bf16 v[4:7], v[210:213], v[232:235], v[4:7]
	v_mfma_f32_16x16x32_bf16 v[0:3], v[210:213], v[236:239], v[0:3]
	ds_read_b128 v[180:183], v215 offset:2048
	ds_read_b128 v[210:213], v215 offset:3072
	s_waitcnt lgkmcnt(2)
	v_mfma_f32_16x16x32_bf16 v[124:127], v[224:227], v[240:243], v[124:127]
	v_mfma_f32_16x16x32_bf16 v[120:123], v[224:227], v[244:247], v[120:123]
	v_mfma_f32_16x16x32_bf16 v[116:119], v[224:227], v[248:251], v[116:119]
	v_mfma_f32_16x16x32_bf16 v[112:115], v[224:227], v[176:179], v[112:115]
	v_mfma_f32_16x16x32_bf16 v[108:111], v[228:231], v[240:243], v[108:111]
	v_mfma_f32_16x16x32_bf16 v[104:107], v[228:231], v[244:247], v[104:107]
	v_mfma_f32_16x16x32_bf16 v[100:103], v[228:231], v[248:251], v[100:103]
	v_mfma_f32_16x16x32_bf16 v[96:99], v[228:231], v[176:179], v[96:99]
	ds_read_b128 v[224:227], v215 offset:4096
	ds_read_b128 v[228:231], v215 offset:5120
	s_waitcnt lgkmcnt(2)
	v_mfma_f32_16x16x32_bf16 v[92:95], v[180:183], v[240:243], v[92:95]
	v_mfma_f32_16x16x32_bf16 v[88:91], v[180:183], v[244:247], v[88:91]
	v_mfma_f32_16x16x32_bf16 v[84:87], v[180:183], v[248:251], v[84:87]
	v_mfma_f32_16x16x32_bf16 v[80:83], v[180:183], v[176:179], v[80:83]
	v_mfma_f32_16x16x32_bf16 v[76:79], v[210:213], v[240:243], v[76:79]
	v_mfma_f32_16x16x32_bf16 v[72:75], v[210:213], v[244:247], v[72:75]
	v_mfma_f32_16x16x32_bf16 v[68:71], v[210:213], v[248:251], v[68:71]
	v_mfma_f32_16x16x32_bf16 v[64:67], v[210:213], v[176:179], v[64:67]
	ds_read_b128 v[180:183], v215 offset:6144
	ds_read_b128 v[210:213], v215 offset:7168
	s_waitcnt lgkmcnt(2)
	v_mfma_f32_16x16x32_bf16 v[60:63], v[224:227], v[240:243], v[60:63]
	v_mfma_f32_16x16x32_bf16 v[56:59], v[224:227], v[244:247], v[56:59]
	v_mfma_f32_16x16x32_bf16 v[52:55], v[224:227], v[248:251], v[52:55]
	v_mfma_f32_16x16x32_bf16 v[48:51], v[224:227], v[176:179], v[48:51]
	v_mfma_f32_16x16x32_bf16 v[44:47], v[228:231], v[240:243], v[44:47]
	v_mfma_f32_16x16x32_bf16 v[40:43], v[228:231], v[244:247], v[40:43]
	v_mfma_f32_16x16x32_bf16 v[36:39], v[228:231], v[248:251], v[36:39]
	v_mfma_f32_16x16x32_bf16 v[32:35], v[228:231], v[176:179], v[32:35]
	s_add_i32 s8, s8, 0x8000
	s_and_b32 s8, s8, 0x18000
	s_waitcnt vmcnt(4) lgkmcnt(0)
	s_barrier
; template <class Epi>
; DI void gemm_tile256(const u16* __restrict__ Ag, long lda, const u16* __restrict__ Bg, long ldb, int nk, char* shm, Epi&& epi) {
;     ...
;   for (int i = 0; i < nk; ++i) {
;     if (i + 2 < nk) asm volatile("s_waitcnt vmcnt(8)" ::: "memory");
;     else if (i + 1 < nk) asm volatile("s_waitcnt vmcnt(4)" ::: "memory");
;     else asm volatile("s_waitcnt vmcnt(0)" ::: "memory");
;     __builtin_amdgcn_s_barrier();
;     const char* SA = shm + (i & 3) * 32768; const char* SB = SA + 16384;
;     bf16x8 At[8], Bt[4];
; #pragma unroll
;     for (int n = 0; n < 4; ++n) { const int rb = wc * 64 + n * 16 + fr; Bt[n] = *reinterpret_cast<const bf16x8*>(SB + rb * 64 + ((fq ^ ((rb >> 2) & 3)) * 16)); }
; #pragma unroll
;     for (int m = 0; m < 8; ++m) { const int ra = wr * 128 + m * 16 + fr; At[m] = *reinterpret_cast<const bf16x8*>(SA + ra * 64 + ((fq ^ ((ra >> 2) & 3)) * 16)); }
;     if (i + 3 < nk) stage(i + 3);
; #pragma unroll
;     for (int m = 0; m < 8; ++m)
; #pragma unroll
;       for (int n = 0; n < 4; ++n) acc[m][n] = __builtin_amdgcn_mfma_f32_16x16x32_bf16(Bt[n], At[m], acc[m][n], 0, 0, 0);
;   }
;   __syncthreads();
	v_add3_u32 v252, v205, v147, s8
	v_add3_u32 v215, v205, v151, s8
	s_nop 0
	ds_read_b128 v[216:219], v252 offset:16384
	ds_read_b128 v[220:223], v252 offset:17408
	ds_read_b128 v[232:235], v252 offset:18432
	ds_read_b128 v[236:239], v252 offset:19456
	ds_read_b128 v[224:227], v215
	ds_read_b128 v[228:231], v215 offset:1024
	v_mfma_f32_16x16x32_bf16 v[28:31], v[180:183], v[240:243], v[28:31]
	v_mfma_f32_16x16x32_bf16 v[24:27], v[180:183], v[244:247], v[24:27]
	v_mfma_f32_16x16x32_bf16 v[20:23], v[180:183], v[248:251], v[20:23]
	v_mfma_f32_16x16x32_bf16 v[16:19], v[180:183], v[176:179], v[16:19]
	v_mfma_f32_16x16x32_bf16 v[12:15], v[210:213], v[240:243], v[12:15]
	v_mfma_f32_16x16x32_bf16 v[8:11], v[210:213], v[244:247], v[8:11]
	v_mfma_f32_16x16x32_bf16 v[4:7], v[210:213], v[248:251], v[4:7]
	v_mfma_f32_16x16x32_bf16 v[0:3], v[210:213], v[176:179], v[0:3]
	ds_read_b128 v[180:183], v215 offset:2048
	ds_read_b128 v[210:213], v215 offset:3072
	s_waitcnt lgkmcnt(2)
	v_mfma_f32_16x16x32_bf16 v[124:127], v[224:227], v[216:219], v[124:127]
	v_mfma_f32_16x16x32_bf16 v[120:123], v[224:227], v[220:223], v[120:123]
	v_mfma_f32_16x16x32_bf16 v[116:119], v[224:227], v[232:235], v[116:119]
	v_mfma_f32_16x16x32_bf16 v[112:115], v[224:227], v[236:239], v[112:115]
	v_mfma_f32_16x16x32_bf16 v[108:111], v[228:231], v[216:219], v[108:111]
	v_mfma_f32_16x16x32_bf16 v[104:107], v[228:231], v[220:223], v[104:107]
	v_mfma_f32_16x16x32_bf16 v[100:103], v[228:231], v[232:235], v[100:103]
	v_mfma_f32_16x16x32_bf16 v[96:99], v[228:231], v[236:239], v[96:99]
	ds_read_b128 v[224:227], v215 offset:4096
	ds_read_b128 v[228:231], v215 offset:5120
	s_waitcnt lgkmcnt(2)
	v_mfma_f32_16x16x32_bf16 v[92:95], v[180:183], v[216:219], v[92:95]
	v_mfma_f32_16x16x32_bf16 v[88:91], v[180:183], v[220:223], v[88:91]
	v_mfma_f32_16x16x32_bf16 v[84:87], v[180:183], v[232:235], v[84:87]
	v_mfma_f32_16x16x32_bf16 v[80:83], v[180:183], v[236:239], v[80:83]
	v_mfma_f32_16x16x32_bf16 v[76:79], v[210:213], v[216:219], v[76:79]
	v_mfma_f32_16x16x32_bf16 v[72:75], v[210:213], v[220:223], v[72:75]
	v_mfma_f32_16x16x32_bf16 v[68:71], v[210:213], v[232:235], v[68:71]
	v_mfma_f32_16x16x32_bf16 v[64:67], v[210:213], v[236:239], v[64:67]
	ds_read_b128 v[180:183], v215 offset:6144
	ds_read_b128 v[210:213], v215 offset:7168
	s_waitcnt lgkmcnt(2)
	v_mfma_f32_16x16x32_bf16 v[60:63], v[224:227], v[216:219], v[60:63]
	v_mfma_f32_16x16x32_bf16 v[56:59], v[224:227], v[220:223], v[56:59]
	v_mfma_f32_16x16x32_bf16 v[52:55], v[224:227], v[232:235], v[52:55]
	v_mfma_f32_16x16x32_bf16 v[48:51], v[224:227], v[236:239], v[48:51]
	v_mfma_f32_16x16x32_bf16 v[44:47], v[228:231], v[216:219], v[44:47]
	v_mfma_f32_16x16x32_bf16 v[40:43], v[228:231], v[220:223], v[40:43]
	v_mfma_f32_16x16x32_bf16 v[36:39], v[228:231], v[232:235], v[36:39]
	v_mfma_f32_16x16x32_bf16 v[32:35], v[228:231], v[236:239], v[32:35]
	s_add_i32 s8, s8, 0x8000
	s_and_b32 s8, s8, 0x18000
	s_waitcnt vmcnt(0) lgkmcnt(0)
	s_barrier
	v_add3_u32 v252, v205, v147, s8
	v_add3_u32 v215, v205, v151, s8
	s_nop 0
	ds_read_b128 v[240:243], v252 offset:16384
	ds_read_b128 v[244:247], v252 offset:17408
	ds_read_b128 v[248:251], v252 offset:18432
	ds_read_b128 v[176:179], v252 offset:19456
	ds_read_b128 v[224:227], v215
	ds_read_b128 v[228:231], v215 offset:1024
	v_mfma_f32_16x16x32_bf16 v[28:31], v[180:183], v[216:219], v[28:31]
	v_mfma_f32_16x16x32_bf16 v[24:27], v[180:183], v[220:223], v[24:27]
	v_mfma_f32_16x16x32_bf16 v[20:23], v[180:183], v[232:235], v[20:23]
	v_mfma_f32_16x16x32_bf16 v[16:19], v[180:183], v[236:239], v[16:19]
	v_mfma_f32_16x16x32_bf16 v[12:15], v[210:213], v[216:219], v[12:15]
	v_mfma_f32_16x16x32_bf16 v[8:11], v[210:213], v[220:223], v[8:11]
	v_mfma_f32_16x16x32_bf16 v[4:7], v[210:213], v[232:235], v[4:7]
	v_mfma_f32_16x16x32_bf16 v[0:3], v[210:213], v[236:239], v[0:3]
	ds_read_b128 v[180:183], v215 offset:2048
	ds_read_b128 v[210:213], v215 offset:3072
	s_waitcnt lgkmcnt(2)
	v_mfma_f32_16x16x32_bf16 v[124:127], v[224:227], v[240:243], v[124:127]
	v_mfma_f32_16x16x32_bf16 v[120:123], v[224:227], v[244:247], v[120:123]
	v_mfma_f32_16x16x32_bf16 v[116:119], v[224:227], v[248:251], v[116:119]
	v_mfma_f32_16x16x32_bf16 v[112:115], v[224:227], v[176:179], v[112:115]
	v_mfma_f32_16x16x32_bf16 v[108:111], v[228:231], v[240:243], v[108:111]
	v_mfma_f32_16x16x32_bf16 v[104:107], v[228:231], v[244:247], v[104:107]
	v_mfma_f32_16x16x32_bf16 v[100:103], v[228:231], v[248:251], v[100:103]
	v_mfma_f32_16x16x32_bf16 v[96:99], v[228:231], v[176:179], v[96:99]
	ds_read_b128 v[224:227], v215 offset:4096
	ds_read_b128 v[228:231], v215 offset:5120
	s_waitcnt lgkmcnt(2)
	v_mfma_f32_16x16x32_bf16 v[92:95], v[180:183], v[240:243], v[92:95]
	v_mfma_f32_16x16x32_bf16 v[88:91], v[180:183], v[244:247], v[88:91]
	v_mfma_f32_16x16x32_bf16 v[84:87], v[180:183], v[248:251], v[84:87]
	v_mfma_f32_16x16x32_bf16 v[80:83], v[180:183], v[176:179], v[80:83]
	v_mfma_f32_16x16x32_bf16 v[76:79], v[210:213], v[240:243], v[76:79]
	v_mfma_f32_16x16x32_bf16 v[72:75], v[210:213], v[244:247], v[72:75]
	v_mfma_f32_16x16x32_bf16 v[68:71], v[210:213], v[248:251], v[68:71]
	v_mfma_f32_16x16x32_bf16 v[64:67], v[210:213], v[176:179], v[64:67]
	ds_read_b128 v[180:183], v215 offset:6144
	ds_read_b128 v[210:213], v215 offset:7168
	s_waitcnt lgkmcnt(2)
	v_mfma_f32_16x16x32_bf16 v[60:63], v[224:227], v[240:243], v[60:63]
	v_mfma_f32_16x16x32_bf16 v[56:59], v[224:227], v[244:247], v[56:59]
	v_mfma_f32_16x16x32_bf16 v[52:55], v[224:227], v[248:251], v[52:55]
	v_mfma_f32_16x16x32_bf16 v[48:51], v[224:227], v[176:179], v[48:51]
	v_mfma_f32_16x16x32_bf16 v[44:47], v[228:231], v[240:243], v[44:47]
	v_mfma_f32_16x16x32_bf16 v[40:43], v[228:231], v[244:247], v[40:43]
	v_mfma_f32_16x16x32_bf16 v[36:39], v[228:231], v[248:251], v[36:39]
	v_mfma_f32_16x16x32_bf16 v[32:35], v[228:231], v[176:179], v[32:35]
	s_waitcnt lgkmcnt(0)
	v_mfma_f32_16x16x32_bf16 v[28:31], v[180:183], v[240:243], v[28:31]
	v_mfma_f32_16x16x32_bf16 v[24:27], v[180:183], v[244:247], v[24:27]
	v_mfma_f32_16x16x32_bf16 v[20:23], v[180:183], v[248:251], v[20:23]
	v_mfma_f32_16x16x32_bf16 v[16:19], v[180:183], v[176:179], v[16:19]
	v_mfma_f32_16x16x32_bf16 v[12:15], v[210:213], v[240:243], v[12:15]
	v_mfma_f32_16x16x32_bf16 v[8:11], v[210:213], v[244:247], v[8:11]
	v_mfma_f32_16x16x32_bf16 v[4:7], v[210:213], v[248:251], v[4:7]
	v_mfma_f32_16x16x32_bf16 v[0:3], v[210:213], v[176:179], v[0:3]
	s_setprio 0
	s_nop 7
	s_nop 3
	s_waitcnt vmcnt(0) lgkmcnt(0)
	s_barrier
; DI u16 f2bf(float x) { return (u16)(pack2bf(x, 0.f) & 0xffffu); }
; template <class Epi>
; DI void gemm_tile256(const u16* __restrict__ Ag, long lda, const u16* __restrict__ Bg, long ldb, int nk, char* shm, Epi&& epi) {
;     ...
;   for (int m = 0; m < 8; ++m)
; #pragma unroll
;     for (int n = 0; n < 4; ++n) epi(wr * 128 + m * 16 + fr, wc * 64 + n * 16 + fq * 4, acc[m][n]);
; DI void phase1(const Params& P, char* smem) {
;     ...
;         const int hd = c - 1536, b = r >> 13, l = r & 8191;
; #pragma unroll
;         for (int j = 0; j < 4; ++j) Vt[((long)(b * 512 + hd + j)) * 8192 + l] = f2bf(v[j]);
	v_and_b32_e32 v184, 15, v208
	v_lshrrev_b32_e32 v185, 4, v208
	v_lshrrev_b32_e32 v186, 6, v189
	v_lshlrev_b32_e32 v186, 14, v186
	v_lshrrev_b32_e32 v206, 1, v185
	v_and_b32_e32 v207, 1, v185
	v_lshl_add_u32 v215, v184, 8, v186
	v_lshl_add_u32 v215, v207, 3, v215
	v_or_b32_e32 v252, 0, v206
	v_xor_b32_e32 v252, v252, v184
	v_lshl_add_u32 v176, v252, 4, v215
	v_or_b32_e32 v252, 2, v206
	v_xor_b32_e32 v252, v252, v184
	v_lshl_add_u32 v177, v252, 4, v215
	v_or_b32_e32 v252, 4, v206
	v_xor_b32_e32 v252, v252, v184
	v_lshl_add_u32 v178, v252, 4, v215
	v_or_b32_e32 v252, 6, v206
	v_xor_b32_e32 v252, v252, v184
	v_lshl_add_u32 v179, v252, 4, v215
	v_or_b32_e32 v252, 8, v206
	v_xor_b32_e32 v252, v252, v184
	v_lshl_add_u32 v180, v252, 4, v215
	v_or_b32_e32 v252, 10, v206
	v_xor_b32_e32 v252, v252, v184
	v_lshl_add_u32 v181, v252, 4, v215
	v_or_b32_e32 v252, 12, v206
	v_xor_b32_e32 v252, v252, v184
	v_lshl_add_u32 v211, v252, 4, v215
	v_or_b32_e32 v252, 14, v206
	v_xor_b32_e32 v252, v252, v184
	v_lshl_add_u32 v242, v252, 4, v215
	v_add_u32_e32 v253, 0, v185
	v_xor_b32_e32 v252, v184, v253
	v_lshl_add_u32 v243, v253, 8, v186
	v_lshl_add_u32 v243, v252, 4, v243
	v_add_u32_e32 v253, 4, v185
	v_xor_b32_e32 v252, v184, v253
	v_lshl_add_u32 v212, v253, 8, v186
	v_lshl_add_u32 v212, v252, 4, v212
	v_add_u32_e32 v253, 8, v185
	v_xor_b32_e32 v252, v184, v253
	v_lshl_add_u32 v213, v253, 8, v186
	v_lshl_add_u32 v213, v252, 4, v213
	v_add_u32_e32 v253, 12, v185
	v_xor_b32_e32 v252, v184, v253
	v_lshl_add_u32 v187, v253, 8, v186
	v_lshl_add_u32 v187, v252, 4, v187
	v_bfe_u32 v252, v189, 6, 2
	v_lshl_add_u32 v252, v252, 6, v185
	s_lshr_b32 s36, s30, 13
	s_lshl_b32 s36, s36, 9
	s_and_b32 s37, s74, 1
	s_lshl_b32 s37, s37, 8
	s_add_i32 s36, s36, s37
	v_add_u32_e32 v252, s36, v252
	v_lshlrev_b32_e32 v182, 14, v252
	s_and_b32 s36, s30, 0x1fff
	v_lshl_add_u32 v252, v190, 7, s36
	v_lshl_add_u32 v182, v252, 1, v182
	v_lshl_add_u32 v182, v184, 4, v182
	v_mov_b32_e32 v183, 0
	v_lshl_add_u64 v[182:183], v[182:183], 0, s[62:63]
	s_mov_b32 s38, 0x10000
	s_mov_b32 s39, 0
	v_lshl_add_u64 v[240:241], v[182:183], 0, s[38:39]
	s_lshl_b32 s38, s38, 1
	v_cvt_pk_bf16_f32 v124, v124, v125
	v_cvt_pk_bf16_f32 v125, v126, v127
	ds_write_b64 v176, v[124:125] offset:0
	v_cvt_pk_bf16_f32 v120, v120, v121
	v_cvt_pk_bf16_f32 v121, v122, v123
	ds_write_b64 v176, v[120:121] offset:4096
	v_cvt_pk_bf16_f32 v116, v116, v117
	v_cvt_pk_bf16_f32 v117, v118, v119
	ds_write_b64 v176, v[116:117] offset:8192
	v_cvt_pk_bf16_f32 v112, v112, v113
	v_cvt_pk_bf16_f32 v113, v114, v115
	ds_write_b64 v176, v[112:113] offset:12288
	v_cvt_pk_bf16_f32 v108, v108, v109
	v_cvt_pk_bf16_f32 v109, v110, v111
	ds_write_b64 v177, v[108:109] offset:0
	v_cvt_pk_bf16_f32 v104, v104, v105
	v_cvt_pk_bf16_f32 v105, v106, v107
	ds_write_b64 v177, v[104:105] offset:4096
	v_cvt_pk_bf16_f32 v100, v100, v101
	v_cvt_pk_bf16_f32 v101, v102, v103
	ds_write_b64 v177, v[100:101] offset:8192
	v_cvt_pk_bf16_f32 v96, v96, v97
	v_cvt_pk_bf16_f32 v97, v98, v99
	ds_write_b64 v177, v[96:97] offset:12288
	v_cvt_pk_bf16_f32 v92, v92, v93
	v_cvt_pk_bf16_f32 v93, v94, v95
	ds_write_b64 v178, v[92:93] offset:0
	v_cvt_pk_bf16_f32 v88, v88, v89
	v_cvt_pk_bf16_f32 v89, v90, v91
	ds_write_b64 v178, v[88:89] offset:4096
	v_cvt_pk_bf16_f32 v84, v84, v85
	v_cvt_pk_bf16_f32 v85, v86, v87
	ds_write_b64 v178, v[84:85] offset:8192
	v_cvt_pk_bf16_f32 v80, v80, v81
	v_cvt_pk_bf16_f32 v81, v82, v83
	ds_write_b64 v178, v[80:81] offset:12288
	v_cvt_pk_bf16_f32 v76, v76, v77
	v_cvt_pk_bf16_f32 v77, v78, v79
	ds_write_b64 v179, v[76:77] offset:0
	v_cvt_pk_bf16_f32 v72, v72, v73
	v_cvt_pk_bf16_f32 v73, v74, v75
	ds_write_b64 v179, v[72:73] offset:4096
	v_cvt_pk_bf16_f32 v68, v68, v69
	v_cvt_pk_bf16_f32 v69, v70, v71
	ds_write_b64 v179, v[68:69] offset:8192
	v_cvt_pk_bf16_f32 v64, v64, v65
	v_cvt_pk_bf16_f32 v65, v66, v67
	ds_write_b64 v179, v[64:65] offset:12288
	v_cvt_pk_bf16_f32 v60, v60, v61
	v_cvt_pk_bf16_f32 v61, v62, v63
	ds_write_b64 v180, v[60:61] offset:0
	v_cvt_pk_bf16_f32 v56, v56, v57
	v_cvt_pk_bf16_f32 v57, v58, v59
	ds_write_b64 v180, v[56:57] offset:4096
	v_cvt_pk_bf16_f32 v52, v52, v53
	v_cvt_pk_bf16_f32 v53, v54, v55
	ds_write_b64 v180, v[52:53] offset:8192
	v_cvt_pk_bf16_f32 v48, v48, v49
	v_cvt_pk_bf16_f32 v49, v50, v51
	ds_write_b64 v180, v[48:49] offset:12288
	v_cvt_pk_bf16_f32 v44, v44, v45
	v_cvt_pk_bf16_f32 v45, v46, v47
	ds_write_b64 v181, v[44:45] offset:0
	v_cvt_pk_bf16_f32 v40, v40, v41
	v_cvt_pk_bf16_f32 v41, v42, v43
	ds_write_b64 v181, v[40:41] offset:4096
	v_cvt_pk_bf16_f32 v36, v36, v37
	v_cvt_pk_bf16_f32 v37, v38, v39
	ds_write_b64 v181, v[36:37] offset:8192
	v_cvt_pk_bf16_f32 v32, v32, v33
	v_cvt_pk_bf16_f32 v33, v34, v35
	ds_write_b64 v181, v[32:33] offset:12288
	v_cvt_pk_bf16_f32 v28, v28, v29
	v_cvt_pk_bf16_f32 v29, v30, v31
	ds_write_b64 v211, v[28:29] offset:0
	v_cvt_pk_bf16_f32 v24, v24, v25
	v_cvt_pk_bf16_f32 v25, v26, v27
	ds_write_b64 v211, v[24:25] offset:4096
	v_cvt_pk_bf16_f32 v20, v20, v21
	v_cvt_pk_bf16_f32 v21, v22, v23
	ds_write_b64 v211, v[20:21] offset:8192
	v_cvt_pk_bf16_f32 v16, v16, v17
	v_cvt_pk_bf16_f32 v17, v18, v19
	ds_write_b64 v211, v[16:17] offset:12288
	v_cvt_pk_bf16_f32 v12, v12, v13
	v_cvt_pk_bf16_f32 v13, v14, v15
	ds_write_b64 v242, v[12:13] offset:0
	v_cvt_pk_bf16_f32 v8, v8, v9
	v_cvt_pk_bf16_f32 v9, v10, v11
	ds_write_b64 v242, v[8:9] offset:4096
	v_cvt_pk_bf16_f32 v4, v4, v5
	v_cvt_pk_bf16_f32 v5, v6, v7
	ds_write_b64 v242, v[4:5] offset:8192
	v_cvt_pk_bf16_f32 v0, v0, v1
	v_cvt_pk_bf16_f32 v1, v2, v3
	ds_write_b64 v242, v[0:1] offset:12288
	s_waitcnt lgkmcnt(0)
; DI u16 f2bf(float x) { return (u16)(pack2bf(x, 0.f) & 0xffffu); }
; DI void phase1(const Params& P, char* smem) {
;     ...
;   for (int q = RBLK >> 3; q < 128; q += RGRID >> 3) {
;     ...
;         const int hd = c - 1536, b = r >> 13, l = r & 8191;
; #pragma unroll
;         for (int j = 0; j < 4; ++j) Vt[((long)(b * 512 + hd + j)) * 8192 + l] = f2bf(v[j]);
	ds_read_b128 v[216:219], v243 offset:0
	ds_read_b128 v[220:223], v212 offset:0
	ds_read_b128 v[224:227], v213 offset:0
	ds_read_b128 v[228:231], v187 offset:0
	s_waitcnt lgkmcnt(3)
	global_store_dwordx4 v[182:183], v[216:219], off
	s_nop 0
	v_lshl_add_u64 v[182:183], v[182:183], 0, s[38:39]
	s_waitcnt lgkmcnt(2)
	global_store_dwordx4 v[240:241], v[220:223], off
	s_nop 0
	v_lshl_add_u64 v[240:241], v[240:241], 0, s[38:39]
	s_waitcnt lgkmcnt(1)
	global_store_dwordx4 v[182:183], v[224:227], off
	s_nop 0
	v_lshl_add_u64 v[182:183], v[182:183], 0, s[38:39]
	s_waitcnt lgkmcnt(0)
	global_store_dwordx4 v[240:241], v[228:231], off
	s_nop 0
	v_lshl_add_u64 v[240:241], v[240:241], 0, s[38:39]
	ds_read_b128 v[232:235], v243 offset:4096
	ds_read_b128 v[236:239], v212 offset:4096
	ds_read_b128 v[244:247], v213 offset:4096
	ds_read_b128 v[248:251], v187 offset:4096
	s_waitcnt lgkmcnt(3)
	global_store_dwordx4 v[182:183], v[232:235], off
	s_nop 0
	v_lshl_add_u64 v[182:183], v[182:183], 0, s[38:39]
	s_waitcnt lgkmcnt(2)
	global_store_dwordx4 v[240:241], v[236:239], off
	s_nop 0
	v_lshl_add_u64 v[240:241], v[240:241], 0, s[38:39]
	s_waitcnt lgkmcnt(1)
	global_store_dwordx4 v[182:183], v[244:247], off
	s_nop 0
	v_lshl_add_u64 v[182:183], v[182:183], 0, s[38:39]
	s_waitcnt lgkmcnt(0)
	global_store_dwordx4 v[240:241], v[248:251], off
	s_nop 0
	v_lshl_add_u64 v[240:241], v[240:241], 0, s[38:39]
	ds_read_b128 v[216:219], v243 offset:8192
	ds_read_b128 v[220:223], v212 offset:8192
	ds_read_b128 v[224:227], v213 offset:8192
	ds_read_b128 v[228:231], v187 offset:8192
	s_waitcnt lgkmcnt(3)
	global_store_dwordx4 v[182:183], v[216:219], off
	s_nop 0
	v_lshl_add_u64 v[182:183], v[182:183], 0, s[38:39]
	s_waitcnt lgkmcnt(2)
	global_store_dwordx4 v[240:241], v[220:223], off
	s_nop 0
	v_lshl_add_u64 v[240:241], v[240:241], 0, s[38:39]
	s_waitcnt lgkmcnt(1)
	global_store_dwordx4 v[182:183], v[224:227], off
	s_nop 0
	v_lshl_add_u64 v[182:183], v[182:183], 0, s[38:39]
	s_waitcnt lgkmcnt(0)
	global_store_dwordx4 v[240:241], v[228:231], off
	s_nop 0
	v_lshl_add_u64 v[240:241], v[240:241], 0, s[38:39]
	ds_read_b128 v[232:235], v243 offset:12288
	ds_read_b128 v[236:239], v212 offset:12288
	ds_read_b128 v[244:247], v213 offset:12288
	ds_read_b128 v[248:251], v187 offset:12288
	s_waitcnt lgkmcnt(3)
	global_store_dwordx4 v[182:183], v[232:235], off
	s_nop 0
	v_lshl_add_u64 v[182:183], v[182:183], 0, s[38:39]
	s_waitcnt lgkmcnt(2)
	global_store_dwordx4 v[240:241], v[236:239], off
	s_nop 0
	v_lshl_add_u64 v[240:241], v[240:241], 0, s[38:39]
	s_waitcnt lgkmcnt(1)
	global_store_dwordx4 v[182:183], v[244:247], off
	s_nop 0
	v_lshl_add_u64 v[182:183], v[182:183], 0, s[38:39]
	s_waitcnt lgkmcnt(0)
	global_store_dwordx4 v[240:241], v[248:251], off
	s_nop 0
	v_lshl_add_u64 v[240:241], v[240:241], 0, s[38:39]
	v_or_b32_e32 v212, 0x50, v153
	v_or_b32_e32 v213, 0x60, v153
	s_branch .LBB0_106

; template <class Epi>
; DI void gemm_tile256(const u16* __restrict__ Ag, long lda, const u16* __restrict__ Bg, long ldb, int nk, char* shm, Epi&& epi) {
;     ...
;   for (int i = 0; i < nk; ++i) {
;     if (i + 2 < nk) asm volatile("s_waitcnt vmcnt(8)" ::: "memory");
;     else if (i + 1 < nk) asm volatile("s_waitcnt vmcnt(4)" ::: "memory");
;     else asm volatile("s_waitcnt vmcnt(0)" ::: "memory");
;     __builtin_amdgcn_s_barrier();
;     const char* SA = shm + (i & 3) * 32768; const char* SB = SA + 16384;
;     bf16x8 At[8], Bt[4];
; #pragma unroll
;     for (int n = 0; n < 4; ++n) { const int rb = wc * 64 + n * 16 + fr; Bt[n] = *reinterpret_cast<const bf16x8*>(SB + rb * 64 + ((fq ^ ((rb >> 2) & 3)) * 16)); }
; #pragma unroll
;     for (int m = 0; m < 8; ++m) { const int ra = wr * 128 + m * 16 + fr; At[m] = *reinterpret_cast<const bf16x8*>(SA + ra * 64 + ((fq ^ ((ra >> 2) & 3)) * 16)); }
;     if (i + 3 < nk) stage(i + 3);
; #pragma unroll
;     for (int m = 0; m < 8; ++m)
; #pragma unroll
;       for (int n = 0; n < 4; ++n) acc[m][n] = __builtin_amdgcn_mfma_f32_16x16x32_bf16(Bt[n], At[m], acc[m][n], 0, 0, 0);
;   }
.Lgemm_p1_kloopn:
	s_add_i32 s6, s8, 0x18000
	s_and_b32 s6, s6, 0x18000
	s_add_i32 s9, s6, s7
	ds_read_b128 v[180:183], v215 offset:2048
	ds_read_b128 v[210:213], v215 offset:3072
	s_waitcnt lgkmcnt(2)
	v_mfma_f32_16x16x32_bf16 v[124:127], v[216:219], v[224:227], v[124:127]
	v_lshl_add_u64 v[206:207], v[184:185], 0, s[4:5]
	v_mfma_f32_16x16x32_bf16 v[120:123], v[220:223], v[224:227], v[120:123]
	s_mov_b32 m0, s9
	v_mfma_f32_16x16x32_bf16 v[116:119], v[232:235], v[224:227], v[116:119]
	s_add_i32 s9, s9, 0x2000
	v_mfma_f32_16x16x32_bf16 v[112:115], v[236:239], v[224:227], v[112:115]
	global_load_lds_dwordx4 v[206:207], off
	v_mfma_f32_16x16x32_bf16 v[108:111], v[216:219], v[228:231], v[108:111]
	v_mfma_f32_16x16x32_bf16 v[104:107], v[220:223], v[228:231], v[104:107]
	v_mfma_f32_16x16x32_bf16 v[100:103], v[232:235], v[228:231], v[100:103]
	v_mfma_f32_16x16x32_bf16 v[96:99], v[236:239], v[228:231], v[96:99]
	ds_read_b128 v[224:227], v215 offset:4096
	ds_read_b128 v[228:231], v215 offset:5120
	s_waitcnt lgkmcnt(2)
	v_mfma_f32_16x16x32_bf16 v[92:95], v[216:219], v[180:183], v[92:95]
	v_lshl_add_u64 v[206:207], v[186:187], 0, s[4:5]
	v_mfma_f32_16x16x32_bf16 v[88:91], v[220:223], v[180:183], v[88:91]
	s_mov_b32 m0, s9
	v_mfma_f32_16x16x32_bf16 v[84:87], v[232:235], v[180:183], v[84:87]
	s_add_i32 s9, s9, 0x2000
	v_mfma_f32_16x16x32_bf16 v[80:83], v[236:239], v[180:183], v[80:83]
	global_load_lds_dwordx4 v[206:207], off
	v_mfma_f32_16x16x32_bf16 v[76:79], v[216:219], v[210:213], v[76:79]
	v_mfma_f32_16x16x32_bf16 v[72:75], v[220:223], v[210:213], v[72:75]
	v_mfma_f32_16x16x32_bf16 v[68:71], v[232:235], v[210:213], v[68:71]
	v_mfma_f32_16x16x32_bf16 v[64:67], v[236:239], v[210:213], v[64:67]
	ds_read_b128 v[180:183], v215 offset:6144
	ds_read_b128 v[210:213], v215 offset:7168
	s_waitcnt lgkmcnt(2)
	v_mfma_f32_16x16x32_bf16 v[60:63], v[216:219], v[224:227], v[60:63]
	v_lshl_add_u64 v[206:207], v[172:173], 0, s[4:5]
	v_mfma_f32_16x16x32_bf16 v[56:59], v[220:223], v[224:227], v[56:59]
	s_mov_b32 m0, s9
	v_mfma_f32_16x16x32_bf16 v[52:55], v[232:235], v[224:227], v[52:55]
	s_add_i32 s9, s9, 0x2000
	v_mfma_f32_16x16x32_bf16 v[48:51], v[236:239], v[224:227], v[48:51]
	global_load_lds_dwordx4 v[206:207], off
	v_mfma_f32_16x16x32_bf16 v[44:47], v[216:219], v[228:231], v[44:47]
	v_mfma_f32_16x16x32_bf16 v[40:43], v[220:223], v[228:231], v[40:43]
	v_mfma_f32_16x16x32_bf16 v[36:39], v[232:235], v[228:231], v[36:39]
	v_mfma_f32_16x16x32_bf16 v[32:35], v[236:239], v[228:231], v[32:35]
	s_add_i32 s8, s8, 0x8000
	s_and_b32 s8, s8, 0x18000
	s_waitcnt vmcnt(7) lgkmcnt(0)
	s_barrier
	v_add3_u32 v252, v205, v147, s8
	v_add3_u32 v215, v205, v151, s8
	s_nop 0
	ds_read_b128 v[240:243], v252 offset:16384
	ds_read_b128 v[244:247], v252 offset:17408
	ds_read_b128 v[248:251], v252 offset:18432
	ds_read_b128 v[176:179], v252 offset:19456
	ds_read_b128 v[224:227], v215
	ds_read_b128 v[228:231], v215 offset:1024
	v_mfma_f32_16x16x32_bf16 v[28:31], v[216:219], v[180:183], v[28:31]
	v_lshl_add_u64 v[206:207], v[174:175], 0, s[4:5]
	v_mfma_f32_16x16x32_bf16 v[24:27], v[220:223], v[180:183], v[24:27]
	s_mov_b32 m0, s9
	v_mfma_f32_16x16x32_bf16 v[20:23], v[232:235], v[180:183], v[20:23]
	s_add_i32 s9, s9, 0x2000
	v_mfma_f32_16x16x32_bf16 v[16:19], v[236:239], v[180:183], v[16:19]
	global_load_lds_dwordx4 v[206:207], off
	v_mfma_f32_16x16x32_bf16 v[12:15], v[216:219], v[210:213], v[12:15]
	s_add_u32 s4, s4, 64
	v_mfma_f32_16x16x32_bf16 v[8:11], v[220:223], v[210:213], v[8:11]
	s_addc_u32 s5, s5, 0
	v_mfma_f32_16x16x32_bf16 v[4:7], v[232:235], v[210:213], v[4:7]
	v_mfma_f32_16x16x32_bf16 v[0:3], v[236:239], v[210:213], v[0:3]
	s_add_i32 s6, s8, 0x18000
	s_and_b32 s6, s6, 0x18000
	s_add_i32 s9, s6, s7
	ds_read_b128 v[180:183], v215 offset:2048
	ds_read_b128 v[210:213], v215 offset:3072
	s_waitcnt lgkmcnt(2)
	v_mfma_f32_16x16x32_bf16 v[124:127], v[240:243], v[224:227], v[124:127]
	v_lshl_add_u64 v[206:207], v[184:185], 0, s[4:5]
	v_mfma_f32_16x16x32_bf16 v[120:123], v[244:247], v[224:227], v[120:123]
	s_mov_b32 m0, s9
	v_mfma_f32_16x16x32_bf16 v[116:119], v[248:251], v[224:227], v[116:119]
	s_add_i32 s9, s9, 0x2000
	v_mfma_f32_16x16x32_bf16 v[112:115], v[176:179], v[224:227], v[112:115]
	global_load_lds_dwordx4 v[206:207], off
	v_mfma_f32_16x16x32_bf16 v[108:111], v[240:243], v[228:231], v[108:111]
	v_mfma_f32_16x16x32_bf16 v[104:107], v[244:247], v[228:231], v[104:107]
	v_mfma_f32_16x16x32_bf16 v[100:103], v[248:251], v[228:231], v[100:103]
	v_mfma_f32_16x16x32_bf16 v[96:99], v[176:179], v[228:231], v[96:99]
	ds_read_b128 v[224:227], v215 offset:4096
	ds_read_b128 v[228:231], v215 offset:5120
	s_waitcnt lgkmcnt(2)
	v_mfma_f32_16x16x32_bf16 v[92:95], v[240:243], v[180:183], v[92:95]
	v_lshl_add_u64 v[206:207], v[186:187], 0, s[4:5]
	v_mfma_f32_16x16x32_bf16 v[88:91], v[244:247], v[180:183], v[88:91]
	s_mov_b32 m0, s9
	v_mfma_f32_16x16x32_bf16 v[84:87], v[248:251], v[180:183], v[84:87]
	s_add_i32 s9, s9, 0x2000
	v_mfma_f32_16x16x32_bf16 v[80:83], v[176:179], v[180:183], v[80:83]
	global_load_lds_dwordx4 v[206:207], off
	v_mfma_f32_16x16x32_bf16 v[76:79], v[240:243], v[210:213], v[76:79]
	v_mfma_f32_16x16x32_bf16 v[72:75], v[244:247], v[210:213], v[72:75]
	v_mfma_f32_16x16x32_bf16 v[68:71], v[248:251], v[210:213], v[68:71]
	v_mfma_f32_16x16x32_bf16 v[64:67], v[176:179], v[210:213], v[64:67]
	ds_read_b128 v[180:183], v215 offset:6144
	ds_read_b128 v[210:213], v215 offset:7168
	s_waitcnt lgkmcnt(2)
	v_mfma_f32_16x16x32_bf16 v[60:63], v[240:243], v[224:227], v[60:63]
	v_lshl_add_u64 v[206:207], v[172:173], 0, s[4:5]
	v_mfma_f32_16x16x32_bf16 v[56:59], v[244:247], v[224:227], v[56:59]
	s_mov_b32 m0, s9
	v_mfma_f32_16x16x32_bf16 v[52:55], v[248:251], v[224:227], v[52:55]
	s_add_i32 s9, s9, 0x2000
	v_mfma_f32_16x16x32_bf16 v[48:51], v[176:179], v[224:227], v[48:51]
	global_load_lds_dwordx4 v[206:207], off
	v_mfma_f32_16x16x32_bf16 v[44:47], v[240:243], v[228:231], v[44:47]
	v_mfma_f32_16x16x32_bf16 v[40:43], v[244:247], v[228:231], v[40:43]
	v_mfma_f32_16x16x32_bf16 v[36:39], v[248:251], v[228:231], v[36:39]
	v_mfma_f32_16x16x32_bf16 v[32:35], v[176:179], v[228:231], v[32:35]
	s_add_i32 s8, s8, 0x8000
	s_and_b32 s8, s8, 0x18000
	s_waitcnt vmcnt(7) lgkmcnt(0)
	s_barrier
; template <class Epi>
; DI void gemm_tile256(const u16* __restrict__ Ag, long lda, const u16* __restrict__ Bg, long ldb, int nk, char* shm, Epi&& epi) {
;     ...
;   for (int i = 0; i < nk; ++i) {
;     if (i + 2 < nk) asm volatile("s_waitcnt vmcnt(8)" ::: "memory");
;     else if (i + 1 < nk) asm volatile("s_waitcnt vmcnt(4)" ::: "memory");
;     else asm volatile("s_waitcnt vmcnt(0)" ::: "memory");
;     __builtin_amdgcn_s_barrier();
;     const char* SA = shm + (i & 3) * 32768; const char* SB = SA + 16384;
;     bf16x8 At[8], Bt[4];
; #pragma unroll
;     for (int n = 0; n < 4; ++n) { const int rb = wc * 64 + n * 16 + fr; Bt[n] = *reinterpret_cast<const bf16x8*>(SB + rb * 64 + ((fq ^ ((rb >> 2) & 3)) * 16)); }
; #pragma unroll
;     for (int m = 0; m < 8; ++m) { const int ra = wr * 128 + m * 16 + fr; At[m] = *reinterpret_cast<const bf16x8*>(SA + ra * 64 + ((fq ^ ((ra >> 2) & 3)) * 16)); }
;     if (i + 3 < nk) stage(i + 3);
; #pragma unroll
;     for (int m = 0; m < 8; ++m)
; #pragma unroll
;       for (int n = 0; n < 4; ++n) acc[m][n] = __builtin_amdgcn_mfma_f32_16x16x32_bf16(Bt[n], At[m], acc[m][n], 0, 0, 0);
;   }
	v_add3_u32 v252, v205, v147, s8
	v_add3_u32 v215, v205, v151, s8
	s_nop 0
	ds_read_b128 v[216:219], v252 offset:16384
	ds_read_b128 v[220:223], v252 offset:17408
	ds_read_b128 v[232:235], v252 offset:18432
	ds_read_b128 v[236:239], v252 offset:19456
	ds_read_b128 v[224:227], v215
	ds_read_b128 v[228:231], v215 offset:1024
	v_mfma_f32_16x16x32_bf16 v[28:31], v[240:243], v[180:183], v[28:31]
	v_lshl_add_u64 v[206:207], v[174:175], 0, s[4:5]
	v_mfma_f32_16x16x32_bf16 v[24:27], v[244:247], v[180:183], v[24:27]
	s_mov_b32 m0, s9
	v_mfma_f32_16x16x32_bf16 v[20:23], v[248:251], v[180:183], v[20:23]
	s_add_i32 s9, s9, 0x2000
	v_mfma_f32_16x16x32_bf16 v[16:19], v[176:179], v[180:183], v[16:19]
	global_load_lds_dwordx4 v[206:207], off
	v_mfma_f32_16x16x32_bf16 v[12:15], v[240:243], v[210:213], v[12:15]
	s_add_u32 s4, s4, 64
	v_mfma_f32_16x16x32_bf16 v[8:11], v[244:247], v[210:213], v[8:11]
	s_addc_u32 s5, s5, 0
	v_mfma_f32_16x16x32_bf16 v[4:7], v[248:251], v[210:213], v[4:7]
	v_mfma_f32_16x16x32_bf16 v[0:3], v[176:179], v[210:213], v[0:3]
	s_cmpk_lg_i32 s4, 0x700
	s_cbranch_scc1 .Lgemm_p1_kloopn
	s_add_i32 s6, s8, 0x18000
	s_and_b32 s6, s6, 0x18000
	s_add_i32 s9, s6, s7
	ds_read_b128 v[180:183], v215 offset:2048
	ds_read_b128 v[210:213], v215 offset:3072
	s_waitcnt lgkmcnt(2)
	v_mfma_f32_16x16x32_bf16 v[124:127], v[216:219], v[224:227], v[124:127]
	v_lshl_add_u64 v[206:207], v[184:185], 0, s[4:5]
	v_mfma_f32_16x16x32_bf16 v[120:123], v[220:223], v[224:227], v[120:123]
	s_mov_b32 m0, s9
	v_mfma_f32_16x16x32_bf16 v[116:119], v[232:235], v[224:227], v[116:119]
	s_add_i32 s9, s9, 0x2000
	v_mfma_f32_16x16x32_bf16 v[112:115], v[236:239], v[224:227], v[112:115]
	global_load_lds_dwordx4 v[206:207], off
	v_mfma_f32_16x16x32_bf16 v[108:111], v[216:219], v[228:231], v[108:111]
	v_mfma_f32_16x16x32_bf16 v[104:107], v[220:223], v[228:231], v[104:107]
	v_mfma_f32_16x16x32_bf16 v[100:103], v[232:235], v[228:231], v[100:103]
	v_mfma_f32_16x16x32_bf16 v[96:99], v[236:239], v[228:231], v[96:99]
	ds_read_b128 v[224:227], v215 offset:4096
	ds_read_b128 v[228:231], v215 offset:5120
	s_waitcnt lgkmcnt(2)
	v_mfma_f32_16x16x32_bf16 v[92:95], v[216:219], v[180:183], v[92:95]
	v_lshl_add_u64 v[206:207], v[186:187], 0, s[4:5]
	v_mfma_f32_16x16x32_bf16 v[88:91], v[220:223], v[180:183], v[88:91]
	s_mov_b32 m0, s9
	v_mfma_f32_16x16x32_bf16 v[84:87], v[232:235], v[180:183], v[84:87]
	s_add_i32 s9, s9, 0x2000
	v_mfma_f32_16x16x32_bf16 v[80:83], v[236:239], v[180:183], v[80:83]
	global_load_lds_dwordx4 v[206:207], off
	v_mfma_f32_16x16x32_bf16 v[76:79], v[216:219], v[210:213], v[76:79]
	v_mfma_f32_16x16x32_bf16 v[72:75], v[220:223], v[210:213], v[72:75]
	v_mfma_f32_16x16x32_bf16 v[68:71], v[232:235], v[210:213], v[68:71]
	v_mfma_f32_16x16x32_bf16 v[64:67], v[236:239], v[210:213], v[64:67]
	ds_read_b128 v[180:183], v215 offset:6144
	ds_read_b128 v[210:213], v215 offset:7168
	s_waitcnt lgkmcnt(2)
	v_mfma_f32_16x16x32_bf16 v[60:63], v[216:219], v[224:227], v[60:63]
	v_lshl_add_u64 v[206:207], v[172:173], 0, s[4:5]
	v_mfma_f32_16x16x32_bf16 v[56:59], v[220:223], v[224:227], v[56:59]
	s_mov_b32 m0, s9
	v_mfma_f32_16x16x32_bf16 v[52:55], v[232:235], v[224:227], v[52:55]
	s_add_i32 s9, s9, 0x2000
	v_mfma_f32_16x16x32_bf16 v[48:51], v[236:239], v[224:227], v[48:51]
	global_load_lds_dwordx4 v[206:207], off
	v_mfma_f32_16x16x32_bf16 v[44:47], v[216:219], v[228:231], v[44:47]
	v_mfma_f32_16x16x32_bf16 v[40:43], v[220:223], v[228:231], v[40:43]
	v_mfma_f32_16x16x32_bf16 v[36:39], v[232:235], v[228:231], v[36:39]
	v_mfma_f32_16x16x32_bf16 v[32:35], v[236:239], v[228:231], v[32:35]
	s_add_i32 s8, s8, 0x8000
	s_and_b32 s8, s8, 0x18000
	s_waitcnt vmcnt(7) lgkmcnt(0)
	s_barrier
	v_add3_u32 v252, v205, v147, s8
	v_add3_u32 v215, v205, v151, s8
	s_nop 0
	ds_read_b128 v[240:243], v252 offset:16384
	ds_read_b128 v[244:247], v252 offset:17408
	ds_read_b128 v[248:251], v252 offset:18432
	ds_read_b128 v[176:179], v252 offset:19456
	ds_read_b128 v[224:227], v215
	ds_read_b128 v[228:231], v215 offset:1024
	v_mfma_f32_16x16x32_bf16 v[28:31], v[216:219], v[180:183], v[28:31]
	v_lshl_add_u64 v[206:207], v[174:175], 0, s[4:5]
	v_mfma_f32_16x16x32_bf16 v[24:27], v[220:223], v[180:183], v[24:27]
	s_mov_b32 m0, s9
	v_mfma_f32_16x16x32_bf16 v[20:23], v[232:235], v[180:183], v[20:23]
	s_add_i32 s9, s9, 0x2000
	v_mfma_f32_16x16x32_bf16 v[16:19], v[236:239], v[180:183], v[16:19]
	global_load_lds_dwordx4 v[206:207], off
	v_mfma_f32_16x16x32_bf16 v[12:15], v[216:219], v[210:213], v[12:15]
	s_add_u32 s4, s4, 64
	v_mfma_f32_16x16x32_bf16 v[8:11], v[220:223], v[210:213], v[8:11]
	s_addc_u32 s5, s5, 0
	v_mfma_f32_16x16x32_bf16 v[4:7], v[232:235], v[210:213], v[4:7]
	v_mfma_f32_16x16x32_bf16 v[0:3], v[236:239], v[210:213], v[0:3]
	ds_read_b128 v[180:183], v215 offset:2048
	ds_read_b128 v[210:213], v215 offset:3072
	s_waitcnt lgkmcnt(2)
	v_mfma_f32_16x16x32_bf16 v[124:127], v[240:243], v[224:227], v[124:127]
	v_mfma_f32_16x16x32_bf16 v[120:123], v[244:247], v[224:227], v[120:123]
	v_mfma_f32_16x16x32_bf16 v[116:119], v[248:251], v[224:227], v[116:119]
	v_mfma_f32_16x16x32_bf16 v[112:115], v[176:179], v[224:227], v[112:115]
	v_mfma_f32_16x16x32_bf16 v[108:111], v[240:243], v[228:231], v[108:111]
	v_mfma_f32_16x16x32_bf16 v[104:107], v[244:247], v[228:231], v[104:107]
	v_mfma_f32_16x16x32_bf16 v[100:103], v[248:251], v[228:231], v[100:103]
	v_mfma_f32_16x16x32_bf16 v[96:99], v[176:179], v[228:231], v[96:99]
	ds_read_b128 v[224:227], v215 offset:4096
	ds_read_b128 v[228:231], v215 offset:5120
	s_waitcnt lgkmcnt(2)
	v_mfma_f32_16x16x32_bf16 v[92:95], v[240:243], v[180:183], v[92:95]
	v_mfma_f32_16x16x32_bf16 v[88:91], v[244:247], v[180:183], v[88:91]
	v_mfma_f32_16x16x32_bf16 v[84:87], v[248:251], v[180:183], v[84:87]
	v_mfma_f32_16x16x32_bf16 v[80:83], v[176:179], v[180:183], v[80:83]
	v_mfma_f32_16x16x32_bf16 v[76:79], v[240:243], v[210:213], v[76:79]
	v_mfma_f32_16x16x32_bf16 v[72:75], v[244:247], v[210:213], v[72:75]
	v_mfma_f32_16x16x32_bf16 v[68:71], v[248:251], v[210:213], v[68:71]
	v_mfma_f32_16x16x32_bf16 v[64:67], v[176:179], v[210:213], v[64:67]
	ds_read_b128 v[180:183], v215 offset:6144
	ds_read_b128 v[210:213], v215 offset:7168
	s_waitcnt lgkmcnt(2)
	v_mfma_f32_16x16x32_bf16 v[60:63], v[240:243], v[224:227], v[60:63]
	v_mfma_f32_16x16x32_bf16 v[56:59], v[244:247], v[224:227], v[56:59]
	v_mfma_f32_16x16x32_bf16 v[52:55], v[248:251], v[224:227], v[52:55]
	v_mfma_f32_16x16x32_bf16 v[48:51], v[176:179], v[224:227], v[48:51]
	v_mfma_f32_16x16x32_bf16 v[44:47], v[240:243], v[228:231], v[44:47]
	v_mfma_f32_16x16x32_bf16 v[40:43], v[244:247], v[228:231], v[40:43]
	v_mfma_f32_16x16x32_bf16 v[36:39], v[248:251], v[228:231], v[36:39]
	v_mfma_f32_16x16x32_bf16 v[32:35], v[176:179], v[228:231], v[32:35]
	s_add_i32 s8, s8, 0x8000
	s_and_b32 s8, s8, 0x18000
	s_waitcnt vmcnt(4) lgkmcnt(0)
	s_barrier
; template <class Epi>
; DI void gemm_tile256(const u16* __restrict__ Ag, long lda, const u16* __restrict__ Bg, long ldb, int nk, char* shm, Epi&& epi) {
;     ...
;   for (int i = 0; i < nk; ++i) {
;     if (i + 2 < nk) asm volatile("s_waitcnt vmcnt(8)" ::: "memory");
;     else if (i + 1 < nk) asm volatile("s_waitcnt vmcnt(4)" ::: "memory");
;     else asm volatile("s_waitcnt vmcnt(0)" ::: "memory");
;     __builtin_amdgcn_s_barrier();
;     const char* SA = shm + (i & 3) * 32768; const char* SB = SA + 16384;
;     bf16x8 At[8], Bt[4];
; #pragma unroll
;     for (int n = 0; n < 4; ++n) { const int rb = wc * 64 + n * 16 + fr; Bt[n] = *reinterpret_cast<const bf16x8*>(SB + rb * 64 + ((fq ^ ((rb >> 2) & 3)) * 16)); }
; #pragma unroll
;     for (int m = 0; m < 8; ++m) { const int ra = wr * 128 + m * 16 + fr; At[m] = *reinterpret_cast<const bf16x8*>(SA + ra * 64 + ((fq ^ ((ra >> 2) & 3)) * 16)); }
;     if (i + 3 < nk) stage(i + 3);
; #pragma unroll
;     for (int m = 0; m < 8; ++m)
; #pragma unroll
;       for (int n = 0; n < 4; ++n) acc[m][n] = __builtin_amdgcn_mfma_f32_16x16x32_bf16(Bt[n], At[m], acc[m][n], 0, 0, 0);
;   }
;   __syncthreads();
	v_add3_u32 v252, v205, v147, s8
	v_add3_u32 v215, v205, v151, s8
	s_nop 0
	ds_read_b128 v[216:219], v252 offset:16384
	ds_read_b128 v[220:223], v252 offset:17408
	ds_read_b128 v[232:235], v252 offset:18432
	ds_read_b128 v[236:239], v252 offset:19456
	ds_read_b128 v[224:227], v215
	ds_read_b128 v[228:231], v215 offset:1024
	v_mfma_f32_16x16x32_bf16 v[28:31], v[240:243], v[180:183], v[28:31]
	v_mfma_f32_16x16x32_bf16 v[24:27], v[244:247], v[180:183], v[24:27]
	v_mfma_f32_16x16x32_bf16 v[20:23], v[248:251], v[180:183], v[20:23]
	v_mfma_f32_16x16x32_bf16 v[16:19], v[176:179], v[180:183], v[16:19]
	v_mfma_f32_16x16x32_bf16 v[12:15], v[240:243], v[210:213], v[12:15]
	v_mfma_f32_16x16x32_bf16 v[8:11], v[244:247], v[210:213], v[8:11]
	v_mfma_f32_16x16x32_bf16 v[4:7], v[248:251], v[210:213], v[4:7]
	v_mfma_f32_16x16x32_bf16 v[0:3], v[176:179], v[210:213], v[0:3]
	ds_read_b128 v[180:183], v215 offset:2048
	ds_read_b128 v[210:213], v215 offset:3072
	s_waitcnt lgkmcnt(2)
	v_mfma_f32_16x16x32_bf16 v[124:127], v[216:219], v[224:227], v[124:127]
	v_mfma_f32_16x16x32_bf16 v[120:123], v[220:223], v[224:227], v[120:123]
	v_mfma_f32_16x16x32_bf16 v[116:119], v[232:235], v[224:227], v[116:119]
	v_mfma_f32_16x16x32_bf16 v[112:115], v[236:239], v[224:227], v[112:115]
	v_mfma_f32_16x16x32_bf16 v[108:111], v[216:219], v[228:231], v[108:111]
	v_mfma_f32_16x16x32_bf16 v[104:107], v[220:223], v[228:231], v[104:107]
	v_mfma_f32_16x16x32_bf16 v[100:103], v[232:235], v[228:231], v[100:103]
	v_mfma_f32_16x16x32_bf16 v[96:99], v[236:239], v[228:231], v[96:99]
	ds_read_b128 v[224:227], v215 offset:4096
	ds_read_b128 v[228:231], v215 offset:5120
	s_waitcnt lgkmcnt(2)
	v_mfma_f32_16x16x32_bf16 v[92:95], v[216:219], v[180:183], v[92:95]
	v_mfma_f32_16x16x32_bf16 v[88:91], v[220:223], v[180:183], v[88:91]
	v_mfma_f32_16x16x32_bf16 v[84:87], v[232:235], v[180:183], v[84:87]
	v_mfma_f32_16x16x32_bf16 v[80:83], v[236:239], v[180:183], v[80:83]
	v_mfma_f32_16x16x32_bf16 v[76:79], v[216:219], v[210:213], v[76:79]
	v_mfma_f32_16x16x32_bf16 v[72:75], v[220:223], v[210:213], v[72:75]
	v_mfma_f32_16x16x32_bf16 v[68:71], v[232:235], v[210:213], v[68:71]
	v_mfma_f32_16x16x32_bf16 v[64:67], v[236:239], v[210:213], v[64:67]
	ds_read_b128 v[180:183], v215 offset:6144
	ds_read_b128 v[210:213], v215 offset:7168
	s_waitcnt lgkmcnt(2)
	v_mfma_f32_16x16x32_bf16 v[60:63], v[216:219], v[224:227], v[60:63]
	v_mfma_f32_16x16x32_bf16 v[56:59], v[220:223], v[224:227], v[56:59]
	v_mfma_f32_16x16x32_bf16 v[52:55], v[232:235], v[224:227], v[52:55]
	v_mfma_f32_16x16x32_bf16 v[48:51], v[236:239], v[224:227], v[48:51]
	v_mfma_f32_16x16x32_bf16 v[44:47], v[216:219], v[228:231], v[44:47]
	v_mfma_f32_16x16x32_bf16 v[40:43], v[220:223], v[228:231], v[40:43]
	v_mfma_f32_16x16x32_bf16 v[36:39], v[232:235], v[228:231], v[36:39]
	v_mfma_f32_16x16x32_bf16 v[32:35], v[236:239], v[228:231], v[32:35]
	s_add_i32 s8, s8, 0x8000
	s_and_b32 s8, s8, 0x18000
	s_waitcnt vmcnt(0) lgkmcnt(0)
	s_barrier
	v_add3_u32 v252, v205, v147, s8
	v_add3_u32 v215, v205, v151, s8
	s_nop 0
	ds_read_b128 v[240:243], v252 offset:16384
	ds_read_b128 v[244:247], v252 offset:17408
	ds_read_b128 v[248:251], v252 offset:18432
	ds_read_b128 v[176:179], v252 offset:19456
	ds_read_b128 v[224:227], v215
	ds_read_b128 v[228:231], v215 offset:1024
	v_mfma_f32_16x16x32_bf16 v[28:31], v[216:219], v[180:183], v[28:31]
	v_mfma_f32_16x16x32_bf16 v[24:27], v[220:223], v[180:183], v[24:27]
	v_mfma_f32_16x16x32_bf16 v[20:23], v[232:235], v[180:183], v[20:23]
	v_mfma_f32_16x16x32_bf16 v[16:19], v[236:239], v[180:183], v[16:19]
	v_mfma_f32_16x16x32_bf16 v[12:15], v[216:219], v[210:213], v[12:15]
	v_mfma_f32_16x16x32_bf16 v[8:11], v[220:223], v[210:213], v[8:11]
	v_mfma_f32_16x16x32_bf16 v[4:7], v[232:235], v[210:213], v[4:7]
	v_mfma_f32_16x16x32_bf16 v[0:3], v[236:239], v[210:213], v[0:3]
	ds_read_b128 v[180:183], v215 offset:2048
	ds_read_b128 v[210:213], v215 offset:3072
	s_waitcnt lgkmcnt(2)
	v_mfma_f32_16x16x32_bf16 v[124:127], v[240:243], v[224:227], v[124:127]
	v_mfma_f32_16x16x32_bf16 v[120:123], v[244:247], v[224:227], v[120:123]
	v_mfma_f32_16x16x32_bf16 v[116:119], v[248:251], v[224:227], v[116:119]
	v_mfma_f32_16x16x32_bf16 v[112:115], v[176:179], v[224:227], v[112:115]
	v_mfma_f32_16x16x32_bf16 v[108:111], v[240:243], v[228:231], v[108:111]
	v_mfma_f32_16x16x32_bf16 v[104:107], v[244:247], v[228:231], v[104:107]
	v_mfma_f32_16x16x32_bf16 v[100:103], v[248:251], v[228:231], v[100:103]
	v_mfma_f32_16x16x32_bf16 v[96:99], v[176:179], v[228:231], v[96:99]
	ds_read_b128 v[224:227], v215 offset:4096
	ds_read_b128 v[228:231], v215 offset:5120
	s_waitcnt lgkmcnt(2)
	v_mfma_f32_16x16x32_bf16 v[92:95], v[240:243], v[180:183], v[92:95]
	v_mfma_f32_16x16x32_bf16 v[88:91], v[244:247], v[180:183], v[88:91]
	v_mfma_f32_16x16x32_bf16 v[84:87], v[248:251], v[180:183], v[84:87]
	v_mfma_f32_16x16x32_bf16 v[80:83], v[176:179], v[180:183], v[80:83]
	v_mfma_f32_16x16x32_bf16 v[76:79], v[240:243], v[210:213], v[76:79]
	v_mfma_f32_16x16x32_bf16 v[72:75], v[244:247], v[210:213], v[72:75]
	v_mfma_f32_16x16x32_bf16 v[68:71], v[248:251], v[210:213], v[68:71]
	v_mfma_f32_16x16x32_bf16 v[64:67], v[176:179], v[210:213], v[64:67]
	ds_read_b128 v[180:183], v215 offset:6144
	ds_read_b128 v[210:213], v215 offset:7168
	s_waitcnt lgkmcnt(2)
	v_mfma_f32_16x16x32_bf16 v[60:63], v[240:243], v[224:227], v[60:63]
	v_mfma_f32_16x16x32_bf16 v[56:59], v[244:247], v[224:227], v[56:59]
	v_mfma_f32_16x16x32_bf16 v[52:55], v[248:251], v[224:227], v[52:55]
	v_mfma_f32_16x16x32_bf16 v[48:51], v[176:179], v[224:227], v[48:51]
	v_mfma_f32_16x16x32_bf16 v[44:47], v[240:243], v[228:231], v[44:47]
	v_mfma_f32_16x16x32_bf16 v[40:43], v[244:247], v[228:231], v[40:43]
	v_mfma_f32_16x16x32_bf16 v[36:39], v[248:251], v[228:231], v[36:39]
	v_mfma_f32_16x16x32_bf16 v[32:35], v[176:179], v[228:231], v[32:35]
	s_waitcnt lgkmcnt(0)
	v_mfma_f32_16x16x32_bf16 v[28:31], v[240:243], v[180:183], v[28:31]
	v_mfma_f32_16x16x32_bf16 v[24:27], v[244:247], v[180:183], v[24:27]
	v_mfma_f32_16x16x32_bf16 v[20:23], v[248:251], v[180:183], v[20:23]
	v_mfma_f32_16x16x32_bf16 v[16:19], v[176:179], v[180:183], v[16:19]
	v_mfma_f32_16x16x32_bf16 v[12:15], v[240:243], v[210:213], v[12:15]
	v_mfma_f32_16x16x32_bf16 v[8:11], v[244:247], v[210:213], v[8:11]
	v_mfma_f32_16x16x32_bf16 v[4:7], v[248:251], v[210:213], v[4:7]
	v_mfma_f32_16x16x32_bf16 v[0:3], v[176:179], v[210:213], v[0:3]
	s_setprio 0
	s_nop 7
	s_nop 3
	s_and_b64 vcc, exec, s[10:11]
	s_cbranch_vccz .Lgemm_p1_u
; DI unsigned pack2bf(float a, float b) { const f2_t v = {a, b}; return __builtin_bit_cast(unsigned, __builtin_convertvector(v, bf2_t)); }
; template <class Epi>
; DI void gemm_tile256(const u16* __restrict__ Ag, long lda, const u16* __restrict__ Bg, long ldb, int nk, char* shm, Epi&& epi) {
;     ...
;   for (int m = 0; m < 8; ++m)
; #pragma unroll
;     for (int n = 0; n < 4; ++n) epi(wr * 128 + m * 16 + fr, wc * 64 + n * 16 + fq * 4, acc[m][n]);
; DI void phase1(const Params& P, char* smem) {
;     ...
;     gemm_tile256(xb + (long)brow * 1024, 1024, WinT + (long)bcol * 1024, 1024, 32, smem, [&](int row, int col0, f32x4 v) {
;       const int r = brow + row, c = bcol + col0;
;       const uint2 pk = make_uint2(pack2bf(v[0], v[1]), pack2bf(v[2], v[3]));
;       if (bcol < 512) {
;         const int g = c >> 4, hp = c & 15, m = r >> 6, j = r & 63;
;         *reinterpret_cast<uint2*>(UG + ((long)g * 512 + m) * UGLD + j * 16 + hp) = pk;
;       } else if (bcol < 1024) {
;         *reinterpret_cast<uint2*>(Qb + (long)r * 512 + (c - 512)) = pk;
;       } else if (bcol < 1536) {
;         *reinterpret_cast<uint2*>(Kb + (long)r * 512 + (c - 1024)) = pk;
	s_waitcnt vmcnt(0) lgkmcnt(0)
	s_barrier
	v_and_b32_e32 v184, 15, v208
	v_lshrrev_b32_e32 v185, 4, v208
	v_lshrrev_b32_e32 v186, 6, v189
	v_lshlrev_b32_e32 v186, 14, v186
	v_and_b32_e32 v187, 7, v184
	v_lshrrev_b32_e32 v206, 1, v185
	v_and_b32_e32 v207, 1, v185
	v_lshl_add_u32 v215, v184, 7, v186
	v_lshl_add_u32 v215, v207, 3, v215
	v_or_b32_e32 v252, 0, v206
	v_xor_b32_e32 v252, v252, v187
	v_lshl_add_u32 v176, v252, 4, v215
	v_or_b32_e32 v252, 2, v206
	v_xor_b32_e32 v252, v252, v187
	v_lshl_add_u32 v177, v252, 4, v215
	v_or_b32_e32 v252, 4, v206
	v_xor_b32_e32 v252, v252, v187
	v_lshl_add_u32 v178, v252, 4, v215
	v_or_b32_e32 v252, 6, v206
	v_xor_b32_e32 v252, v252, v187
	v_lshl_add_u32 v179, v252, 4, v215
	v_lshrrev_b32_e32 v253, 3, v208
	v_and_b32_e32 v210, 7, v208
	v_xor_b32_e32 v252, v210, v253
	v_lshl_add_u32 v180, v253, 7, v186
	v_lshl_add_u32 v180, v252, 4, v180
	v_lshl_add_u32 v252, v190, 7, v253
	v_add_u32_e32 v252, s30, v252
	v_lshlrev_b32_e32 v182, 10, v252
	v_bfe_u32 v252, v189, 6, 2
	v_lshl_add_u32 v182, v252, 7, v182
	v_lshl_add_u32 v182, v210, 4, v182
	v_mov_b32_e32 v183, 0
	s_and_b32 s36, s74, 1
	s_lshl_b32 s36, s36, 9
	s_and_b32 s37, s74, 4
	s_lshl_b32 s37, s37, 23
	s_add_u32 s36, s36, s37
	s_add_u32 s36, s78, s36
	s_addc_u32 s37, s79, 0
	v_lshl_add_u64 v[182:183], v[182:183], 0, s[36:37]
	s_mov_b32 s38, 0x2000
	s_mov_b32 s39, 0
	v_lshl_add_u64 v[240:241], v[182:183], 0, s[38:39]
	s_lshl_b32 s38, s38, 1
	v_cvt_pk_bf16_f32 v124, v124, v125
	v_cvt_pk_bf16_f32 v125, v126, v127
	ds_write_b64 v176, v[124:125] offset:0
	v_cvt_pk_bf16_f32 v120, v120, v121
	v_cvt_pk_bf16_f32 v121, v122, v123
	ds_write_b64 v177, v[120:121] offset:0
	v_cvt_pk_bf16_f32 v116, v116, v117
	v_cvt_pk_bf16_f32 v117, v118, v119
	ds_write_b64 v178, v[116:117] offset:0
	v_cvt_pk_bf16_f32 v112, v112, v113
	v_cvt_pk_bf16_f32 v113, v114, v115
	ds_write_b64 v179, v[112:113] offset:0
	v_cvt_pk_bf16_f32 v108, v108, v109
	v_cvt_pk_bf16_f32 v109, v110, v111
	ds_write_b64 v176, v[108:109] offset:2048
	v_cvt_pk_bf16_f32 v104, v104, v105
	v_cvt_pk_bf16_f32 v105, v106, v107
	ds_write_b64 v177, v[104:105] offset:2048
	v_cvt_pk_bf16_f32 v100, v100, v101
	v_cvt_pk_bf16_f32 v101, v102, v103
	ds_write_b64 v178, v[100:101] offset:2048
	v_cvt_pk_bf16_f32 v96, v96, v97
	v_cvt_pk_bf16_f32 v97, v98, v99
	ds_write_b64 v179, v[96:97] offset:2048
	v_cvt_pk_bf16_f32 v92, v92, v93
	v_cvt_pk_bf16_f32 v93, v94, v95
	ds_write_b64 v176, v[92:93] offset:4096
	v_cvt_pk_bf16_f32 v88, v88, v89
	v_cvt_pk_bf16_f32 v89, v90, v91
	ds_write_b64 v177, v[88:89] offset:4096
	v_cvt_pk_bf16_f32 v84, v84, v85
	v_cvt_pk_bf16_f32 v85, v86, v87
	ds_write_b64 v178, v[84:85] offset:4096
	v_cvt_pk_bf16_f32 v80, v80, v81
	v_cvt_pk_bf16_f32 v81, v82, v83
	ds_write_b64 v179, v[80:81] offset:4096
	v_cvt_pk_bf16_f32 v76, v76, v77
	v_cvt_pk_bf16_f32 v77, v78, v79
	ds_write_b64 v176, v[76:77] offset:6144
	v_cvt_pk_bf16_f32 v72, v72, v73
	v_cvt_pk_bf16_f32 v73, v74, v75
	ds_write_b64 v177, v[72:73] offset:6144
	v_cvt_pk_bf16_f32 v68, v68, v69
	v_cvt_pk_bf16_f32 v69, v70, v71
	ds_write_b64 v178, v[68:69] offset:6144
	v_cvt_pk_bf16_f32 v64, v64, v65
	v_cvt_pk_bf16_f32 v65, v66, v67
	ds_write_b64 v179, v[64:65] offset:6144
	v_cvt_pk_bf16_f32 v60, v60, v61
	v_cvt_pk_bf16_f32 v61, v62, v63
	ds_write_b64 v176, v[60:61] offset:8192
	v_cvt_pk_bf16_f32 v56, v56, v57
	v_cvt_pk_bf16_f32 v57, v58, v59
	ds_write_b64 v177, v[56:57] offset:8192
	v_cvt_pk_bf16_f32 v52, v52, v53
	v_cvt_pk_bf16_f32 v53, v54, v55
	ds_write_b64 v178, v[52:53] offset:8192
	v_cvt_pk_bf16_f32 v48, v48, v49
	v_cvt_pk_bf16_f32 v49, v50, v51
	ds_write_b64 v179, v[48:49] offset:8192
	v_cvt_pk_bf16_f32 v44, v44, v45
	v_cvt_pk_bf16_f32 v45, v46, v47
	ds_write_b64 v176, v[44:45] offset:10240
	v_cvt_pk_bf16_f32 v40, v40, v41
	v_cvt_pk_bf16_f32 v41, v42, v43
	ds_write_b64 v177, v[40:41] offset:10240
	v_cvt_pk_bf16_f32 v36, v36, v37
	v_cvt_pk_bf16_f32 v37, v38, v39
	ds_write_b64 v178, v[36:37] offset:10240
	v_cvt_pk_bf16_f32 v32, v32, v33
	v_cvt_pk_bf16_f32 v33, v34, v35
	ds_write_b64 v179, v[32:33] offset:10240
	v_cvt_pk_bf16_f32 v28, v28, v29
	v_cvt_pk_bf16_f32 v29, v30, v31
	ds_write_b64 v176, v[28:29] offset:12288
	v_cvt_pk_bf16_f32 v24, v24, v25
	v_cvt_pk_bf16_f32 v25, v26, v27
	ds_write_b64 v177, v[24:25] offset:12288
	v_cvt_pk_bf16_f32 v20, v20, v21
	v_cvt_pk_bf16_f32 v21, v22, v23
	ds_write_b64 v178, v[20:21] offset:12288
	v_cvt_pk_bf16_f32 v16, v16, v17
	v_cvt_pk_bf16_f32 v17, v18, v19
	ds_write_b64 v179, v[16:17] offset:12288
	v_cvt_pk_bf16_f32 v12, v12, v13
	v_cvt_pk_bf16_f32 v13, v14, v15
	ds_write_b64 v176, v[12:13] offset:14336
	v_cvt_pk_bf16_f32 v8, v8, v9
	v_cvt_pk_bf16_f32 v9, v10, v11
	ds_write_b64 v177, v[8:9] offset:14336
	v_cvt_pk_bf16_f32 v4, v4, v5
	v_cvt_pk_bf16_f32 v5, v6, v7
	ds_write_b64 v178, v[4:5] offset:14336
	v_cvt_pk_bf16_f32 v0, v0, v1
	v_cvt_pk_bf16_f32 v1, v2, v3
	ds_write_b64 v179, v[0:1] offset:14336
	s_waitcnt lgkmcnt(0)
; DI void phase1(const Params& P, char* smem) {
;     ...
;       } else if (bcol < 1024) {
;         *reinterpret_cast<uint2*>(Qb + (long)r * 512 + (c - 512)) = pk;
;       } else if (bcol < 1536) {
;         *reinterpret_cast<uint2*>(Kb + (long)r * 512 + (c - 1024)) = pk;
	ds_read_b128 v[216:219], v180 offset:0
	ds_read_b128 v[220:223], v180 offset:1024
	ds_read_b128 v[224:227], v180 offset:2048
	ds_read_b128 v[228:231], v180 offset:3072
	s_waitcnt lgkmcnt(3)
	global_store_dwordx4 v[182:183], v[216:219], off
	s_nop 0
	v_lshl_add_u64 v[182:183], v[182:183], 0, s[38:39]
	s_waitcnt lgkmcnt(2)
	global_store_dwordx4 v[240:241], v[220:223], off
	s_nop 0
	v_lshl_add_u64 v[240:241], v[240:241], 0, s[38:39]
	s_waitcnt lgkmcnt(1)
	global_store_dwordx4 v[182:183], v[224:227], off
	s_nop 0
	v_lshl_add_u64 v[182:183], v[182:183], 0, s[38:39]
	s_waitcnt lgkmcnt(0)
	global_store_dwordx4 v[240:241], v[228:231], off
	s_nop 0
	v_lshl_add_u64 v[240:241], v[240:241], 0, s[38:39]
	ds_read_b128 v[232:235], v180 offset:4096
	ds_read_b128 v[236:239], v180 offset:5120
	ds_read_b128 v[244:247], v180 offset:6144
	ds_read_b128 v[248:251], v180 offset:7168
	s_waitcnt lgkmcnt(3)
	global_store_dwordx4 v[182:183], v[232:235], off
	s_nop 0
	v_lshl_add_u64 v[182:183], v[182:183], 0, s[38:39]
	s_waitcnt lgkmcnt(2)
	global_store_dwordx4 v[240:241], v[236:239], off
	s_nop 0
	v_lshl_add_u64 v[240:241], v[240:241], 0, s[38:39]
	s_waitcnt lgkmcnt(1)
	global_store_dwordx4 v[182:183], v[244:247], off
	s_nop 0
	v_lshl_add_u64 v[182:183], v[182:183], 0, s[38:39]
	s_waitcnt lgkmcnt(0)
	global_store_dwordx4 v[240:241], v[248:251], off
	s_nop 0
	v_lshl_add_u64 v[240:241], v[240:241], 0, s[38:39]
	ds_read_b128 v[216:219], v180 offset:8192
	ds_read_b128 v[220:223], v180 offset:9216
	ds_read_b128 v[224:227], v180 offset:10240
	ds_read_b128 v[228:231], v180 offset:11264
	s_waitcnt lgkmcnt(3)
	global_store_dwordx4 v[182:183], v[216:219], off
	s_nop 0
	v_lshl_add_u64 v[182:183], v[182:183], 0, s[38:39]
	s_waitcnt lgkmcnt(2)
	global_store_dwordx4 v[240:241], v[220:223], off
	s_nop 0
	v_lshl_add_u64 v[240:241], v[240:241], 0, s[38:39]
	s_waitcnt lgkmcnt(1)
	global_store_dwordx4 v[182:183], v[224:227], off
	s_nop 0
	v_lshl_add_u64 v[182:183], v[182:183], 0, s[38:39]
	s_waitcnt lgkmcnt(0)
	global_store_dwordx4 v[240:241], v[228:231], off
	s_nop 0
	v_lshl_add_u64 v[240:241], v[240:241], 0, s[38:39]
	ds_read_b128 v[232:235], v180 offset:12288
	ds_read_b128 v[236:239], v180 offset:13312
	ds_read_b128 v[244:247], v180 offset:14336
	ds_read_b128 v[248:251], v180 offset:15360
	s_waitcnt lgkmcnt(3)
	global_store_dwordx4 v[182:183], v[232:235], off
	s_nop 0
	v_lshl_add_u64 v[182:183], v[182:183], 0, s[38:39]
	s_waitcnt lgkmcnt(2)
	global_store_dwordx4 v[240:241], v[236:239], off
	s_nop 0
	v_lshl_add_u64 v[240:241], v[240:241], 0, s[38:39]
	s_waitcnt lgkmcnt(1)
	global_store_dwordx4 v[182:183], v[244:247], off
	s_nop 0
	v_lshl_add_u64 v[182:183], v[182:183], 0, s[38:39]
	s_waitcnt lgkmcnt(0)
	global_store_dwordx4 v[240:241], v[248:251], off
	s_nop 0
	v_lshl_add_u64 v[240:241], v[240:241], 0, s[38:39]
	v_or_b32_e32 v212, 0x50, v153
	v_or_b32_e32 v213, 0x60, v153
	s_branch .LBB0_106

; template <class Epi>
; DI void gemm_tile256(const u16* __restrict__ Ag, long lda, const u16* __restrict__ Bg, long ldb, int nk, char* shm, Epi&& epi) {
;   const int tid = RTID, wid = tid >> 6, lane = tid & 63, wr = wid >> 2, wc = wid & 3, fr = lane & 15, fq = lane >> 4;
;   f32x4 acc[8][4];
; #pragma unroll
;   for (int m = 0; m < 8; ++m)
; #pragma unroll
;     for (int n = 0; n < 4; ++n) acc[m][n] = f32x4{0.f, 0.f, 0.f, 0.f};
;   const int q0 = tid, q1 = 512 + tid;
;   const int r0 = q0 >> 2, r1 = q1 >> 2, c0 = (q0 & 3) ^ ((r0 >> 2) & 3), c1 = (q1 & 3) ^ ((r1 >> 2) & 3);
;   const u16* a0 = Ag + (long)r0 * lda + c0 * 8; const u16* a1 = Ag + (long)r1 * lda + c1 * 8;
;   const u16* b0 = Bg + (long)r0 * ldb + c0 * 8; const u16* b1 = Bg + (long)r1 * ldb + c1 * 8;
;   auto stage = [&](int j) {
;     char* SA = shm + (j & 3) * 32768; char* SB = SA + 16384;
;     __builtin_amdgcn_global_load_lds((const unsigned*)(a0 + j * 32), (__attribute__((address_space(3))) unsigned*)(SA + q0 * 16), 16, 0, 0);
;     __builtin_amdgcn_global_load_lds((const unsigned*)(a1 + j * 32), (__attribute__((address_space(3))) unsigned*)(SA + q1 * 16), 16, 0, 0);
;     __builtin_amdgcn_global_load_lds((const unsigned*)(b0 + j * 32), (__attribute__((address_space(3))) unsigned*)(SB + q0 * 16), 16, 0, 0);
;     __builtin_amdgcn_global_load_lds((const unsigned*)(b1 + j * 32), (__attribute__((address_space(3))) unsigned*)(SB + q1 * 16), 16, 0, 0);
;   };
;   __syncthreads();
;   stage(0);
;   if (nk > 1) stage(1);
;   if (nk > 2) stage(2);
;   for (int i = 0; i < nk; ++i) {
;     if (i + 2 < nk) asm volatile("s_waitcnt vmcnt(8)" ::: "memory");
;     else if (i + 1 < nk) asm volatile("s_waitcnt vmcnt(4)" ::: "memory");
;     else asm volatile("s_waitcnt vmcnt(0)" ::: "memory");
;     __builtin_amdgcn_s_barrier();
;     const char* SA = shm + (i & 3) * 32768; const char* SB = SA + 16384;
;     bf16x8 At[8], Bt[4];
; #pragma unroll
; DI void phase6(const Params& P, char* smem) {
;     ...
;   for (int q = RBLK >> 3; q < 64; q += RGRID >> 3) {
;     const int brow = (q * 2 + ((RBLK & 7) >> 2)) * 256, bcol = (RBLK & 3) * 256;
;     gemm_tile256(cat + (long)brow * 1024, 1024, WoT + (long)bcol * 1024, 1024, 32, smem, [&](int row, int col0, f32x4 v) {
.LBB0_946:
	s_ashr_i32 s5, s4, 31
	s_lshl_b64 s[10:11], s[4:5], 11
	s_lshl_b32 s5, s15, 9
	v_lshl_add_u64 v[164:165], v[156:157], 0, s[10:11]
	v_lshl_add_u64 v[166:167], v[158:159], 0, s[10:11]
	s_or_b32 s10, s5, s2
	s_ashr_i32 s11, s10, 31
	s_lshl_b64 s[12:13], s[10:11], 11
	s_add_u32 s12, s62, s12
	s_addc_u32 s13, s63, s13
	v_add_u32_e32 v6, 0, v209
	v_lshl_add_u64 v[0:1], s[12:13], 0, v[130:131]
	v_readfirstlane_b32 s5, v6
	v_add_u32_e32 v7, 0, v149
	v_lshl_add_u64 v[0:1], v[0:1], 0, v[132:133]
	v_lshl_add_u64 v[2:3], s[12:13], 0, v[134:135]
	s_mov_b32 m0, s5
	v_readfirstlane_b32 s5, v7
	v_add_u32_e32 v4, 0x4000, v6
	v_lshl_add_u64 v[2:3], v[2:3], 0, v[132:133]
	s_barrier
	global_load_lds_dwordx4 v[0:1], off
	s_mov_b32 m0, s5
	v_readfirstlane_b32 s5, v4
	v_add_u32_e32 v4, 0x4000, v7
	global_load_lds_dwordx4 v[2:3], off
	s_mov_b32 m0, s5
	v_readfirstlane_b32 s5, v4
	v_add_u32_e32 v8, 0x8000, v6
	global_load_lds_dwordx4 v[136:137], off
	s_mov_b32 m0, s5
	v_readfirstlane_b32 s5, v8
	v_add_u32_e32 v8, 0x8000, v7
	global_load_lds_dwordx4 v[138:139], off
	v_lshl_add_u64 v[4:5], v[0:1], 0, 64
	s_mov_b32 m0, s5
	v_readfirstlane_b32 s5, v8
	global_load_lds_dwordx4 v[4:5], off
	v_lshl_add_u64 v[4:5], v[2:3], 0, 64
	s_mov_b32 m0, s5
	v_lshl_add_u64 v[0:1], v[0:1], 0, s[0:1]
	global_load_lds_dwordx4 v[4:5], off
	v_add_u32_e32 v4, 0xc000, v6
	s_mov_b64 s[12:13], 0
	v_readfirstlane_b32 s5, v4
	v_add_u32_e32 v4, 0xc000, v7
	s_mov_b32 m0, s5
	v_readfirstlane_b32 s5, v4
	v_add_u32_e32 v4, s7, v209
	global_load_lds_dwordx4 v[140:141], off
	s_mov_b32 m0, s5
	v_readfirstlane_b32 s5, v4
	global_load_lds_dwordx4 v[142:143], off
	s_mov_b32 m0, s5
	v_mov_b32_e32 v4, 0
	global_load_lds_dwordx4 v[0:1], off
	v_lshl_add_u64 v[0:1], v[2:3], 0, s[0:1]
	v_add_u32_e32 v2, s7, v149
	v_mov_b32_e32 v3, v133
	v_readfirstlane_b32 s5, v2
	s_mov_b32 m0, s5
	v_mov_b32_e32 v2, v133
	global_load_lds_dwordx4 v[0:1], off
	v_add_u32_e32 v0, s8, v209
	v_mov_b32_e32 v1, v133
	v_readfirstlane_b32 s5, v0
	v_add_u32_e32 v0, s8, v149
	s_mov_b32 m0, s5
	v_readfirstlane_b32 s5, v0
	global_load_lds_dwordx4 v[144:145], off
	s_mov_b32 m0, s5
	s_mov_b32 s5, 0x18000
	global_load_lds_dwordx4 v[146:147], off
	v_mov_b32_e32 v0, 0
	v_mov_b32_e32 v5, v133
	v_mov_b32_e32 v6, v133
	v_mov_b32_e32 v7, v133
	v_mov_b32_e32 v8, 0
	v_mov_b32_e32 v9, v133
	v_mov_b32_e32 v10, v133
	v_mov_b32_e32 v11, v133
	v_mov_b32_e32 v12, 0
	v_mov_b32_e32 v13, v133
	v_mov_b32_e32 v14, v133
	v_mov_b32_e32 v15, v133
	v_mov_b32_e32 v16, 0
	v_mov_b32_e32 v17, v133
	v_mov_b32_e32 v18, v133
	v_mov_b32_e32 v19, v133
	v_mov_b32_e32 v20, 0
	v_mov_b32_e32 v21, v133
	v_mov_b32_e32 v22, v133
	v_mov_b32_e32 v23, v133
	v_mov_b32_e32 v24, 0
	v_mov_b32_e32 v25, v133
	v_mov_b32_e32 v26, v133
	v_mov_b32_e32 v27, v133
	v_mov_b32_e32 v28, 0
	v_mov_b32_e32 v29, v133
	v_mov_b32_e32 v30, v133
	v_mov_b32_e32 v31, v133
	v_mov_b32_e32 v32, 0
	v_mov_b32_e32 v33, v133
	v_mov_b32_e32 v34, v133
	v_mov_b32_e32 v35, v133
	v_mov_b32_e32 v36, 0
	v_mov_b32_e32 v37, v133
	v_mov_b32_e32 v38, v133
	v_mov_b32_e32 v39, v133
	v_mov_b32_e32 v40, 0
	v_mov_b32_e32 v41, v133
	v_mov_b32_e32 v42, v133
	v_mov_b32_e32 v43, v133
	v_mov_b32_e32 v44, 0
	v_mov_b32_e32 v45, v133
	v_mov_b32_e32 v46, v133
	v_mov_b32_e32 v47, v133
	v_mov_b32_e32 v48, 0
	v_mov_b32_e32 v49, v133
	v_mov_b32_e32 v50, v133
	v_mov_b32_e32 v51, v133
	v_mov_b32_e32 v52, 0
	v_mov_b32_e32 v53, v133
	v_mov_b32_e32 v54, v133
	v_mov_b32_e32 v55, v133
	v_mov_b32_e32 v56, 0
	v_mov_b32_e32 v57, v133
	v_mov_b32_e32 v58, v133
	v_mov_b32_e32 v59, v133
	v_mov_b32_e32 v60, 0
	v_mov_b32_e32 v61, v133
	v_mov_b32_e32 v62, v133
	v_mov_b32_e32 v63, v133
	v_mov_b32_e32 v64, 0
	v_mov_b32_e32 v65, v133
	v_mov_b32_e32 v66, v133
	v_mov_b32_e32 v67, v133
	v_mov_b32_e32 v68, 0
	v_mov_b32_e32 v69, v133
	v_mov_b32_e32 v70, v133
	v_mov_b32_e32 v71, v133
	v_mov_b32_e32 v72, 0
	v_mov_b32_e32 v73, v133
	v_mov_b32_e32 v74, v133
	v_mov_b32_e32 v75, v133
	v_mov_b32_e32 v76, 0
	v_mov_b32_e32 v77, v133
	v_mov_b32_e32 v78, v133
	v_mov_b32_e32 v79, v133
	v_mov_b32_e32 v80, 0
	v_mov_b32_e32 v81, v133
	v_mov_b32_e32 v82, v133
	v_mov_b32_e32 v83, v133
	v_mov_b32_e32 v84, 0
	v_mov_b32_e32 v85, v133
	v_mov_b32_e32 v86, v133
	v_mov_b32_e32 v87, v133
	v_mov_b32_e32 v88, 0
	v_mov_b32_e32 v89, v133
	v_mov_b32_e32 v90, v133
	v_mov_b32_e32 v91, v133
	v_mov_b32_e32 v92, 0
	v_mov_b32_e32 v93, v133
	v_mov_b32_e32 v94, v133
	v_mov_b32_e32 v95, v133
	v_mov_b32_e32 v96, 0
	v_mov_b32_e32 v97, v133
	v_mov_b32_e32 v98, v133
	v_mov_b32_e32 v99, v133
	v_mov_b32_e32 v100, 0
	v_mov_b32_e32 v101, v133
	v_mov_b32_e32 v102, v133
	v_mov_b32_e32 v103, v133
	v_mov_b32_e32 v104, 0
	v_mov_b32_e32 v105, v133
	v_mov_b32_e32 v106, v133
	v_mov_b32_e32 v107, v133
	v_mov_b32_e32 v108, 0
	v_mov_b32_e32 v109, v133
	v_mov_b32_e32 v110, v133
	v_mov_b32_e32 v111, v133
	v_mov_b32_e32 v112, 0
	v_mov_b32_e32 v113, v133
	v_mov_b32_e32 v114, v133
	v_mov_b32_e32 v115, v133
	v_mov_b32_e32 v116, 0
	v_mov_b32_e32 v117, v133
	v_mov_b32_e32 v118, v133
	v_mov_b32_e32 v119, v133
	v_mov_b32_e32 v120, 0
	v_mov_b32_e32 v121, v133
	v_mov_b32_e32 v122, v133
	v_mov_b32_e32 v123, v133
	v_mov_b32_e32 v124, 0
	v_mov_b32_e32 v125, v133
	v_mov_b32_e32 v126, v133
	v_mov_b32_e32 v127, v133
	v_readfirstlane_b32 s16, v209
	s_mov_b32 s5, 0
	s_mov_b64 s[12:13], 0
	s_cmpk_lt_u32 s16, 0x1000
	s_cbranch_scc1 .Lgemm_p6_np
	s_setprio 1
.Lgemm_p6_np:
	s_waitcnt vmcnt(8)
	s_barrier
	v_add3_u32 v231, v183, v151, s5
	v_add3_u32 v230, v183, v153, s5
	s_nop 0
	ds_read_b128 v[196:199], v231 offset:16384
	ds_read_b128 v[200:203], v231 offset:17408
	ds_read_b128 v[214:217], v231 offset:18432
	ds_read_b128 v[218:221], v231 offset:19456
	ds_read_b128 v[204:207], v230
	ds_read_b128 v[210:213], v230 offset:1024

; template <class Epi>
; DI void gemm_tile256(const u16* __restrict__ Ag, long lda, const u16* __restrict__ Bg, long ldb, int nk, char* shm, Epi&& epi) {
;     ...
;   __syncthreads();
; #pragma unroll
;   for (int m = 0; m < 8; ++m)
; #pragma unroll
;     for (int n = 0; n < 4; ++n) epi(wr * 128 + m * 16 + fr, wc * 64 + n * 16 + fq * 4, acc[m][n]);
; DI void phase6(const Params& P, char* smem) {
;     ...
;     gemm_tile256(cat + (long)brow * 1024, 1024, WoT + (long)bcol * 1024, 1024, 32, smem, [&](int row, int col0, f32x4 v) {
;       const long o = (long)(brow + row) * 1024 + bcol + col0;
;       const float4 xs = *reinterpret_cast<const float4*>(P.x + o);
;       *reinterpret_cast<float4*>(Z1 + o) = make_float4(ALPHA * xs.x + v[0], ALPHA * xs.y + v[1], ALPHA * xs.z + v[2], ALPHA * xs.w + v[3]);
;     });
.Lgemm_p6_kend:
	s_setprio 0
	s_nop 7
	s_nop 3
	s_waitcnt vmcnt(0) lgkmcnt(0)
	s_barrier
	v_and_b32_e32 v196, 15, v208
	v_lshrrev_b32_e32 v197, 4, v208
	v_lshrrev_b32_e32 v198, 6, v189
	v_lshlrev_b32_e32 v198, 14, v198
	v_lshl_add_u32 v201, v196, 8, v198
	v_or_b32_e32 v199, 0, v197
	v_xor_b32_e32 v199, v199, v196
	v_lshl_add_u32 v206, v199, 4, v201
	v_or_b32_e32 v199, 4, v197
	v_xor_b32_e32 v199, v199, v196
	v_lshl_add_u32 v207, v199, 4, v201
	v_or_b32_e32 v199, 8, v197
	v_xor_b32_e32 v199, v199, v196
	v_lshl_add_u32 v210, v199, 4, v201
	v_or_b32_e32 v199, 12, v197
	v_xor_b32_e32 v199, v199, v196
	v_lshl_add_u32 v211, v199, 4, v201
	v_add_u32_e32 v200, 0, v197
	v_xor_b32_e32 v199, v196, v200
	v_lshl_add_u32 v212, v200, 8, v198
	v_lshl_add_u32 v212, v199, 4, v212
	v_add_u32_e32 v200, 4, v197
	v_xor_b32_e32 v199, v196, v200
	v_lshl_add_u32 v213, v200, 8, v198
	v_lshl_add_u32 v213, v199, 4, v213
	v_add_u32_e32 v200, 8, v197
	v_xor_b32_e32 v199, v196, v200
	v_lshl_add_u32 v214, v200, 8, v198
	v_lshl_add_u32 v214, v199, 4, v214
	v_add_u32_e32 v200, 12, v197
	v_xor_b32_e32 v199, v196, v200
	v_lshl_add_u32 v215, v200, 8, v198
	v_lshl_add_u32 v215, v199, 4, v215
	v_lshl_add_u32 v199, v190, 7, v197
	v_add_u32_e32 v199, s10, v199
	v_lshlrev_b32_e32 v216, 12, v199
	v_bfe_u32 v199, v189, 6, 2
	v_lshl_add_u32 v216, v199, 8, v216
	v_lshl_add_u32 v216, v196, 4, v216
	s_and_b32 s26, s74, 3
	s_lshl_b32 s26, s26, 10
	v_add_u32_e32 v216, s26, v216
	v_add_u32_e32 v201, 0x0, v216
	global_load_dwordx4 v[218:221], v201, s[52:53]
	v_add_u32_e32 v202, 0x4000, v216
	global_load_dwordx4 v[222:225], v202, s[52:53]
	v_add_u32_e32 v201, 0x8000, v216
	global_load_dwordx4 v[226:229], v201, s[52:53]
	v_add_u32_e32 v202, 0xc000, v216
	global_load_dwordx4 v[230:233], v202, s[52:53]
	v_add_u32_e32 v201, 0x10000, v216
	global_load_dwordx4 v[234:237], v201, s[52:53]
	v_add_u32_e32 v202, 0x14000, v216
	global_load_dwordx4 v[238:241], v202, s[52:53]
	v_add_u32_e32 v201, 0x18000, v216
	global_load_dwordx4 v[242:245], v201, s[52:53]
	v_add_u32_e32 v202, 0x1c000, v216
	global_load_dwordx4 v[246:249], v202, s[52:53]
	ds_write_b128 v206, v[124:127] offset:0
	ds_write_b128 v207, v[120:123] offset:0
	ds_write_b128 v210, v[116:119] offset:0
	ds_write_b128 v211, v[112:115] offset:0
	ds_write_b128 v206, v[108:111] offset:4096
	ds_write_b128 v207, v[104:107] offset:4096
	ds_write_b128 v210, v[100:103] offset:4096
	ds_write_b128 v211, v[96:99] offset:4096
	ds_write_b128 v206, v[92:95] offset:8192
	ds_write_b128 v207, v[88:91] offset:8192
	ds_write_b128 v210, v[84:87] offset:8192
	ds_write_b128 v211, v[80:83] offset:8192
	ds_write_b128 v206, v[76:79] offset:12288
	ds_write_b128 v207, v[72:75] offset:12288
	ds_write_b128 v210, v[68:71] offset:12288
	ds_write_b128 v211, v[64:67] offset:12288
	s_waitcnt lgkmcnt(0)
	v_add_u32_e32 v201, 0x20000, v216
	global_load_dwordx4 v[64:67], v201, s[52:53]
	v_add_u32_e32 v202, 0x24000, v216
	global_load_dwordx4 v[68:71], v202, s[52:53]
	v_add_u32_e32 v201, 0x28000, v216
	global_load_dwordx4 v[72:75], v201, s[52:53]
	v_add_u32_e32 v202, 0x2c000, v216
	global_load_dwordx4 v[76:79], v202, s[52:53]
	v_add_u32_e32 v201, 0x30000, v216
	global_load_dwordx4 v[80:83], v201, s[52:53]
	v_add_u32_e32 v202, 0x34000, v216
	global_load_dwordx4 v[84:87], v202, s[52:53]
	v_add_u32_e32 v201, 0x38000, v216
	global_load_dwordx4 v[88:91], v201, s[52:53]
	v_add_u32_e32 v202, 0x3c000, v216
	global_load_dwordx4 v[92:95], v202, s[52:53]
	ds_read_b128 v[96:99], v212 offset:0
	ds_read_b128 v[100:103], v213 offset:0
	ds_read_b128 v[104:107], v214 offset:0
	ds_read_b128 v[108:111], v215 offset:0
	ds_read_b128 v[112:115], v212 offset:4096
	ds_read_b128 v[116:119], v213 offset:4096
	ds_read_b128 v[120:123], v214 offset:4096
	ds_read_b128 v[124:127], v215 offset:4096
	s_waitcnt vmcnt(8)
	s_waitcnt lgkmcnt(7)
	v_pk_fma_f32 v[218:219], v[218:219], s[6:7], v[96:97] op_sel_hi:[1,0,1]
	v_pk_fma_f32 v[220:221], v[220:221], s[6:7], v[98:99] op_sel_hi:[1,0,1]
	v_add_u32_e32 v201, 0x0, v216
	global_store_dwordx4 v201, v[218:221], s[38:39]
	s_waitcnt lgkmcnt(6)
	v_pk_fma_f32 v[222:223], v[222:223], s[6:7], v[100:101] op_sel_hi:[1,0,1]
	v_pk_fma_f32 v[224:225], v[224:225], s[6:7], v[102:103] op_sel_hi:[1,0,1]
	v_add_u32_e32 v202, 0x4000, v216
	global_store_dwordx4 v202, v[222:225], s[38:39]
	s_waitcnt lgkmcnt(5)
	v_pk_fma_f32 v[226:227], v[226:227], s[6:7], v[104:105] op_sel_hi:[1,0,1]
	v_pk_fma_f32 v[228:229], v[228:229], s[6:7], v[106:107] op_sel_hi:[1,0,1]
	v_add_u32_e32 v201, 0x8000, v216
	global_store_dwordx4 v201, v[226:229], s[38:39]
	s_waitcnt lgkmcnt(4)
	v_pk_fma_f32 v[230:231], v[230:231], s[6:7], v[108:109] op_sel_hi:[1,0,1]
	v_pk_fma_f32 v[232:233], v[232:233], s[6:7], v[110:111] op_sel_hi:[1,0,1]
	v_add_u32_e32 v202, 0xc000, v216
	global_store_dwordx4 v202, v[230:233], s[38:39]
	s_waitcnt lgkmcnt(3)
	v_pk_fma_f32 v[234:235], v[234:235], s[6:7], v[112:113] op_sel_hi:[1,0,1]
	v_pk_fma_f32 v[236:237], v[236:237], s[6:7], v[114:115] op_sel_hi:[1,0,1]
	v_add_u32_e32 v201, 0x10000, v216
	global_store_dwordx4 v201, v[234:237], s[38:39]
	s_waitcnt lgkmcnt(2)
	v_pk_fma_f32 v[238:239], v[238:239], s[6:7], v[116:117] op_sel_hi:[1,0,1]
	v_pk_fma_f32 v[240:241], v[240:241], s[6:7], v[118:119] op_sel_hi:[1,0,1]
	v_add_u32_e32 v202, 0x14000, v216
	global_store_dwordx4 v202, v[238:241], s[38:39]
	s_waitcnt lgkmcnt(1)
	v_pk_fma_f32 v[242:243], v[242:243], s[6:7], v[120:121] op_sel_hi:[1,0,1]
	v_pk_fma_f32 v[244:245], v[244:245], s[6:7], v[122:123] op_sel_hi:[1,0,1]
	v_add_u32_e32 v201, 0x18000, v216
	global_store_dwordx4 v201, v[242:245], s[38:39]
	s_waitcnt lgkmcnt(0)
; DI void phase6(const Params& P, char* smem) {
;     ...
;     gemm_tile256(cat + (long)brow * 1024, 1024, WoT + (long)bcol * 1024, 1024, 32, smem, [&](int row, int col0, f32x4 v) {
;       const long o = (long)(brow + row) * 1024 + bcol + col0;
;       const float4 xs = *reinterpret_cast<const float4*>(P.x + o);
;       *reinterpret_cast<float4*>(Z1 + o) = make_float4(ALPHA * xs.x + v[0], ALPHA * xs.y + v[1], ALPHA * xs.z + v[2], ALPHA * xs.w + v[3]);
;     });
	v_pk_fma_f32 v[246:247], v[246:247], s[6:7], v[124:125] op_sel_hi:[1,0,1]
	v_pk_fma_f32 v[248:249], v[248:249], s[6:7], v[126:127] op_sel_hi:[1,0,1]
	v_add_u32_e32 v202, 0x1c000, v216
	global_store_dwordx4 v202, v[246:249], s[38:39]
	ds_read_b128 v[96:99], v212 offset:8192
	ds_read_b128 v[100:103], v213 offset:8192
	ds_read_b128 v[104:107], v214 offset:8192
	ds_read_b128 v[108:111], v215 offset:8192
	ds_read_b128 v[112:115], v212 offset:12288
	ds_read_b128 v[116:119], v213 offset:12288
	ds_read_b128 v[120:123], v214 offset:12288
	ds_read_b128 v[124:127], v215 offset:12288
	s_waitcnt vmcnt(0)
	s_waitcnt lgkmcnt(7)
	v_pk_fma_f32 v[64:65], v[64:65], s[6:7], v[96:97] op_sel_hi:[1,0,1]
	v_pk_fma_f32 v[66:67], v[66:67], s[6:7], v[98:99] op_sel_hi:[1,0,1]
	v_add_u32_e32 v201, 0x20000, v216
	global_store_dwordx4 v201, v[64:67], s[38:39]
	s_waitcnt lgkmcnt(6)
	v_pk_fma_f32 v[68:69], v[68:69], s[6:7], v[100:101] op_sel_hi:[1,0,1]
	v_pk_fma_f32 v[70:71], v[70:71], s[6:7], v[102:103] op_sel_hi:[1,0,1]
	v_add_u32_e32 v202, 0x24000, v216
	global_store_dwordx4 v202, v[68:71], s[38:39]
	s_waitcnt lgkmcnt(5)
	v_pk_fma_f32 v[72:73], v[72:73], s[6:7], v[104:105] op_sel_hi:[1,0,1]
	v_pk_fma_f32 v[74:75], v[74:75], s[6:7], v[106:107] op_sel_hi:[1,0,1]
	v_add_u32_e32 v201, 0x28000, v216
	global_store_dwordx4 v201, v[72:75], s[38:39]
	s_waitcnt lgkmcnt(4)
	v_pk_fma_f32 v[76:77], v[76:77], s[6:7], v[108:109] op_sel_hi:[1,0,1]
	v_pk_fma_f32 v[78:79], v[78:79], s[6:7], v[110:111] op_sel_hi:[1,0,1]
	v_add_u32_e32 v202, 0x2c000, v216
	global_store_dwordx4 v202, v[76:79], s[38:39]
	s_waitcnt lgkmcnt(3)
	v_pk_fma_f32 v[80:81], v[80:81], s[6:7], v[112:113] op_sel_hi:[1,0,1]
	v_pk_fma_f32 v[82:83], v[82:83], s[6:7], v[114:115] op_sel_hi:[1,0,1]
	v_add_u32_e32 v201, 0x30000, v216
	global_store_dwordx4 v201, v[80:83], s[38:39]
	s_waitcnt lgkmcnt(2)
	v_pk_fma_f32 v[84:85], v[84:85], s[6:7], v[116:117] op_sel_hi:[1,0,1]
	v_pk_fma_f32 v[86:87], v[86:87], s[6:7], v[118:119] op_sel_hi:[1,0,1]
	v_add_u32_e32 v202, 0x34000, v216
	global_store_dwordx4 v202, v[84:87], s[38:39]
	s_waitcnt lgkmcnt(1)
	v_pk_fma_f32 v[88:89], v[88:89], s[6:7], v[120:121] op_sel_hi:[1,0,1]
	v_pk_fma_f32 v[90:91], v[90:91], s[6:7], v[122:123] op_sel_hi:[1,0,1]
	v_add_u32_e32 v201, 0x38000, v216
	global_store_dwordx4 v201, v[88:91], s[38:39]
	s_waitcnt lgkmcnt(0)
	v_pk_fma_f32 v[92:93], v[92:93], s[6:7], v[124:125] op_sel_hi:[1,0,1]
	v_pk_fma_f32 v[94:95], v[94:95], s[6:7], v[126:127] op_sel_hi:[1,0,1]
	v_add_u32_e32 v202, 0x3c000, v216
	global_store_dwordx4 v202, v[92:95], s[38:39]
	s_waitcnt lgkmcnt(0)
	v_add_u32_e32 v201, 0x40000, v216
	global_load_dwordx4 v[218:221], v201, s[52:53]
	v_add_u32_e32 v202, 0x44000, v216
	global_load_dwordx4 v[222:225], v202, s[52:53]
	v_add_u32_e32 v201, 0x48000, v216
	global_load_dwordx4 v[226:229], v201, s[52:53]
	v_add_u32_e32 v202, 0x4c000, v216
	global_load_dwordx4 v[230:233], v202, s[52:53]
	v_add_u32_e32 v201, 0x50000, v216
	global_load_dwordx4 v[234:237], v201, s[52:53]
	v_add_u32_e32 v202, 0x54000, v216
	global_load_dwordx4 v[238:241], v202, s[52:53]
	v_add_u32_e32 v201, 0x58000, v216
	global_load_dwordx4 v[242:245], v201, s[52:53]
	v_add_u32_e32 v202, 0x5c000, v216
	global_load_dwordx4 v[246:249], v202, s[52:53]
	ds_write_b128 v206, v[60:63] offset:0
	ds_write_b128 v207, v[56:59] offset:0
	ds_write_b128 v210, v[52:55] offset:0
	ds_write_b128 v211, v[48:51] offset:0
	ds_write_b128 v206, v[44:47] offset:4096
	ds_write_b128 v207, v[40:43] offset:4096
	ds_write_b128 v210, v[36:39] offset:4096
	ds_write_b128 v211, v[32:35] offset:4096
	ds_write_b128 v206, v[28:31] offset:8192
	ds_write_b128 v207, v[24:27] offset:8192
	ds_write_b128 v210, v[20:23] offset:8192
	ds_write_b128 v211, v[16:19] offset:8192
	ds_write_b128 v206, v[12:15] offset:12288
	ds_write_b128 v207, v[8:11] offset:12288
	ds_write_b128 v210, v[4:7] offset:12288
	ds_write_b128 v211, v[0:3] offset:12288
	s_waitcnt lgkmcnt(0)
	v_add_u32_e32 v201, 0x60000, v216
	global_load_dwordx4 v[64:67], v201, s[52:53]
	v_add_u32_e32 v202, 0x64000, v216
	global_load_dwordx4 v[68:71], v202, s[52:53]
	v_add_u32_e32 v201, 0x68000, v216
	global_load_dwordx4 v[72:75], v201, s[52:53]
	v_add_u32_e32 v202, 0x6c000, v216
	global_load_dwordx4 v[76:79], v202, s[52:53]
	v_add_u32_e32 v201, 0x70000, v216
	global_load_dwordx4 v[80:83], v201, s[52:53]
	v_add_u32_e32 v202, 0x74000, v216
	global_load_dwordx4 v[84:87], v202, s[52:53]
	v_add_u32_e32 v201, 0x78000, v216
	global_load_dwordx4 v[88:91], v201, s[52:53]
	v_add_u32_e32 v202, 0x7c000, v216
	global_load_dwordx4 v[92:95], v202, s[52:53]
	ds_read_b128 v[96:99], v212 offset:0
	ds_read_b128 v[100:103], v213 offset:0
	ds_read_b128 v[104:107], v214 offset:0
	ds_read_b128 v[108:111], v215 offset:0
	ds_read_b128 v[112:115], v212 offset:4096
	ds_read_b128 v[116:119], v213 offset:4096
	ds_read_b128 v[120:123], v214 offset:4096
	ds_read_b128 v[124:127], v215 offset:4096
	s_waitcnt vmcnt(8)
; DI void phase6(const Params& P, char* smem) {
;     ...
;   for (int q = RBLK >> 3; q < 64; q += RGRID >> 3) {
;     const int brow = (q * 2 + ((RBLK & 7) >> 2)) * 256, bcol = (RBLK & 3) * 256;
;     gemm_tile256(cat + (long)brow * 1024, 1024, WoT + (long)bcol * 1024, 1024, 32, smem, [&](int row, int col0, f32x4 v) {
;       const long o = (long)(brow + row) * 1024 + bcol + col0;
;       const float4 xs = *reinterpret_cast<const float4*>(P.x + o);
;       *reinterpret_cast<float4*>(Z1 + o) = make_float4(ALPHA * xs.x + v[0], ALPHA * xs.y + v[1], ALPHA * xs.z + v[2], ALPHA * xs.w + v[3]);
;     });
	s_waitcnt lgkmcnt(7)
	v_pk_fma_f32 v[218:219], v[218:219], s[6:7], v[96:97] op_sel_hi:[1,0,1]
	v_pk_fma_f32 v[220:221], v[220:221], s[6:7], v[98:99] op_sel_hi:[1,0,1]
	v_add_u32_e32 v201, 0x40000, v216
	global_store_dwordx4 v201, v[218:221], s[38:39]
	s_waitcnt lgkmcnt(6)
	v_pk_fma_f32 v[222:223], v[222:223], s[6:7], v[100:101] op_sel_hi:[1,0,1]
	v_pk_fma_f32 v[224:225], v[224:225], s[6:7], v[102:103] op_sel_hi:[1,0,1]
	v_add_u32_e32 v202, 0x44000, v216
	global_store_dwordx4 v202, v[222:225], s[38:39]
	s_waitcnt lgkmcnt(5)
	v_pk_fma_f32 v[226:227], v[226:227], s[6:7], v[104:105] op_sel_hi:[1,0,1]
	v_pk_fma_f32 v[228:229], v[228:229], s[6:7], v[106:107] op_sel_hi:[1,0,1]
	v_add_u32_e32 v201, 0x48000, v216
	global_store_dwordx4 v201, v[226:229], s[38:39]
	s_waitcnt lgkmcnt(4)
	v_pk_fma_f32 v[230:231], v[230:231], s[6:7], v[108:109] op_sel_hi:[1,0,1]
	v_pk_fma_f32 v[232:233], v[232:233], s[6:7], v[110:111] op_sel_hi:[1,0,1]
	v_add_u32_e32 v202, 0x4c000, v216
	global_store_dwordx4 v202, v[230:233], s[38:39]
	s_waitcnt lgkmcnt(3)
	v_pk_fma_f32 v[234:235], v[234:235], s[6:7], v[112:113] op_sel_hi:[1,0,1]
	v_pk_fma_f32 v[236:237], v[236:237], s[6:7], v[114:115] op_sel_hi:[1,0,1]
	v_add_u32_e32 v201, 0x50000, v216
	global_store_dwordx4 v201, v[234:237], s[38:39]
	s_waitcnt lgkmcnt(2)
	v_pk_fma_f32 v[238:239], v[238:239], s[6:7], v[116:117] op_sel_hi:[1,0,1]
	v_pk_fma_f32 v[240:241], v[240:241], s[6:7], v[118:119] op_sel_hi:[1,0,1]
	v_add_u32_e32 v202, 0x54000, v216
	global_store_dwordx4 v202, v[238:241], s[38:39]
	s_waitcnt lgkmcnt(1)
	v_pk_fma_f32 v[242:243], v[242:243], s[6:7], v[120:121] op_sel_hi:[1,0,1]
	v_pk_fma_f32 v[244:245], v[244:245], s[6:7], v[122:123] op_sel_hi:[1,0,1]
	v_add_u32_e32 v201, 0x58000, v216
	global_store_dwordx4 v201, v[242:245], s[38:39]
	s_waitcnt lgkmcnt(0)
	v_pk_fma_f32 v[246:247], v[246:247], s[6:7], v[124:125] op_sel_hi:[1,0,1]
	v_pk_fma_f32 v[248:249], v[248:249], s[6:7], v[126:127] op_sel_hi:[1,0,1]
	v_add_u32_e32 v202, 0x5c000, v216
	global_store_dwordx4 v202, v[246:249], s[38:39]
	ds_read_b128 v[96:99], v212 offset:8192
	ds_read_b128 v[100:103], v213 offset:8192
	ds_read_b128 v[104:107], v214 offset:8192
	ds_read_b128 v[108:111], v215 offset:8192
	ds_read_b128 v[112:115], v212 offset:12288
	ds_read_b128 v[116:119], v213 offset:12288
	ds_read_b128 v[120:123], v214 offset:12288
	ds_read_b128 v[124:127], v215 offset:12288
	s_waitcnt vmcnt(0)
	s_waitcnt lgkmcnt(7)
	v_pk_fma_f32 v[64:65], v[64:65], s[6:7], v[96:97] op_sel_hi:[1,0,1]
	v_pk_fma_f32 v[66:67], v[66:67], s[6:7], v[98:99] op_sel_hi:[1,0,1]
	v_add_u32_e32 v201, 0x60000, v216
	global_store_dwordx4 v201, v[64:67], s[38:39]
	s_waitcnt lgkmcnt(6)
	v_pk_fma_f32 v[68:69], v[68:69], s[6:7], v[100:101] op_sel_hi:[1,0,1]
	v_pk_fma_f32 v[70:71], v[70:71], s[6:7], v[102:103] op_sel_hi:[1,0,1]
	v_add_u32_e32 v202, 0x64000, v216
	global_store_dwordx4 v202, v[68:71], s[38:39]
	s_waitcnt lgkmcnt(5)
	v_pk_fma_f32 v[72:73], v[72:73], s[6:7], v[104:105] op_sel_hi:[1,0,1]
	v_pk_fma_f32 v[74:75], v[74:75], s[6:7], v[106:107] op_sel_hi:[1,0,1]
	v_add_u32_e32 v201, 0x68000, v216
	global_store_dwordx4 v201, v[72:75], s[38:39]
	s_waitcnt lgkmcnt(4)
	v_pk_fma_f32 v[76:77], v[76:77], s[6:7], v[108:109] op_sel_hi:[1,0,1]
	v_pk_fma_f32 v[78:79], v[78:79], s[6:7], v[110:111] op_sel_hi:[1,0,1]
	v_add_u32_e32 v202, 0x6c000, v216
	global_store_dwordx4 v202, v[76:79], s[38:39]
	s_waitcnt lgkmcnt(3)
	v_pk_fma_f32 v[80:81], v[80:81], s[6:7], v[112:113] op_sel_hi:[1,0,1]
	v_pk_fma_f32 v[82:83], v[82:83], s[6:7], v[114:115] op_sel_hi:[1,0,1]
	v_add_u32_e32 v201, 0x70000, v216
	global_store_dwordx4 v201, v[80:83], s[38:39]
	s_waitcnt lgkmcnt(2)
	v_pk_fma_f32 v[84:85], v[84:85], s[6:7], v[116:117] op_sel_hi:[1,0,1]
	v_pk_fma_f32 v[86:87], v[86:87], s[6:7], v[118:119] op_sel_hi:[1,0,1]
	v_add_u32_e32 v202, 0x74000, v216
	global_store_dwordx4 v202, v[84:87], s[38:39]
	s_waitcnt lgkmcnt(1)
	v_pk_fma_f32 v[88:89], v[88:89], s[6:7], v[120:121] op_sel_hi:[1,0,1]
	v_pk_fma_f32 v[90:91], v[90:91], s[6:7], v[122:123] op_sel_hi:[1,0,1]
	v_add_u32_e32 v201, 0x78000, v216
	global_store_dwordx4 v201, v[88:91], s[38:39]
	s_waitcnt lgkmcnt(0)
	v_pk_fma_f32 v[92:93], v[92:93], s[6:7], v[124:125] op_sel_hi:[1,0,1]
	v_pk_fma_f32 v[94:95], v[94:95], s[6:7], v[126:127] op_sel_hi:[1,0,1]
	v_add_u32_e32 v202, 0x7c000, v216
	global_store_dwordx4 v202, v[92:95], s[38:39]
	s_add_i32 s15, s15, s9
	s_add_i32 s4, s4, s14
	s_cmp_lt_i32 s15, 64
	s_cbranch_scc1 .LBB0_946

; template <class Epi>
; DI void gemm_tile256(const u16* __restrict__ Ag, long lda, const u16* __restrict__ Bg, long ldb, int nk, char* shm, Epi&& epi) {
;   const int tid = RTID, wid = tid >> 6, lane = tid & 63, wr = wid >> 2, wc = wid & 3, fr = lane & 15, fq = lane >> 4;
;   f32x4 acc[8][4];
; #pragma unroll
;   for (int m = 0; m < 8; ++m)
; #pragma unroll
;     for (int n = 0; n < 4; ++n) acc[m][n] = f32x4{0.f, 0.f, 0.f, 0.f};
;   const int q0 = tid, q1 = 512 + tid;
;   const int r0 = q0 >> 2, r1 = q1 >> 2, c0 = (q0 & 3) ^ ((r0 >> 2) & 3), c1 = (q1 & 3) ^ ((r1 >> 2) & 3);
;   const u16* a0 = Ag + (long)r0 * lda + c0 * 8; const u16* a1 = Ag + (long)r1 * lda + c1 * 8;
;   const u16* b0 = Bg + (long)r0 * ldb + c0 * 8; const u16* b1 = Bg + (long)r1 * ldb + c1 * 8;
;   auto stage = [&](int j) {
;     char* SA = shm + (j & 3) * 32768; char* SB = SA + 16384;
;     __builtin_amdgcn_global_load_lds((const unsigned*)(a0 + j * 32), (__attribute__((address_space(3))) unsigned*)(SA + q0 * 16), 16, 0, 0);
;     __builtin_amdgcn_global_load_lds((const unsigned*)(a1 + j * 32), (__attribute__((address_space(3))) unsigned*)(SA + q1 * 16), 16, 0, 0);
;     __builtin_amdgcn_global_load_lds((const unsigned*)(b0 + j * 32), (__attribute__((address_space(3))) unsigned*)(SB + q0 * 16), 16, 0, 0);
;     __builtin_amdgcn_global_load_lds((const unsigned*)(b1 + j * 32), (__attribute__((address_space(3))) unsigned*)(SB + q1 * 16), 16, 0, 0);
;   };
;   __syncthreads();
;   stage(0);
;   if (nk > 1) stage(1);
;   if (nk > 2) stage(2);
;   for (int i = 0; i < nk; ++i) {
;     if (i + 2 < nk) asm volatile("s_waitcnt vmcnt(8)" ::: "memory");
;     else if (i + 1 < nk) asm volatile("s_waitcnt vmcnt(4)" ::: "memory");
;     else asm volatile("s_waitcnt vmcnt(0)" ::: "memory");
;     __builtin_amdgcn_s_barrier();
;     const char* SA = shm + (i & 3) * 32768; const char* SB = SA + 16384;
;     bf16x8 At[8], Bt[4];
; #pragma unroll
;     for (int n = 0; n < 4; ++n) { const int rb = wc * 64 + n * 16 + fr; Bt[n] = *reinterpret_cast<const bf16x8*>(SB + rb * 64 + ((fq ^ ((rb >> 2) & 3)) * 16)); }
; #pragma unroll
; DI void phase8(const Params& P, char* smem) {
;     ...
;   for (int q = RBLK >> 3; q < 128; q += RGRID >> 3) {
;     const int brow = q * 256, bcol = (RBLK & 7) * 256;
;     gemm_tile256(h1b + (long)brow * 1024, 1024, WqT + (long)bcol * 1024, 1024, 32, smem, [&](int row, int col0, f32x4 v) {
.LBB0_1068:
	s_ashr_i32 s7, s6, 31
	s_lshl_b64 s[10:11], s[6:7], 11
	v_lshl_add_u64 v[158:159], v[150:151], 0, s[10:11]
	v_lshl_add_u64 v[160:161], v[152:153], 0, s[10:11]
	s_lshl_b32 s10, s75, 8
	s_ashr_i32 s11, s10, 31
	s_lshl_b64 s[12:13], s[10:11], 11
	s_add_u32 s12, s40, s12
	s_addc_u32 s13, s41, s13
	v_add_u32_e32 v6, 0, v209
	v_lshl_add_u64 v[0:1], s[12:13], 0, v[130:131]
	v_readfirstlane_b32 s7, v6
	v_add_u32_e32 v7, 0, v162
	v_lshl_add_u64 v[0:1], v[0:1], 0, v[132:133]
	v_lshl_add_u64 v[2:3], s[12:13], 0, v[134:135]
	s_mov_b32 m0, s7
	v_readfirstlane_b32 s7, v7
	v_add_u32_e32 v4, 0x4000, v6
	v_lshl_add_u64 v[2:3], v[2:3], 0, v[132:133]
	s_barrier
	global_load_lds_dwordx4 v[0:1], off
	s_mov_b32 m0, s7
	v_readfirstlane_b32 s7, v4
	v_add_u32_e32 v4, 0x4000, v7
	global_load_lds_dwordx4 v[2:3], off
	s_mov_b32 m0, s7
	v_readfirstlane_b32 s7, v4
	v_add_u32_e32 v8, 0x8000, v6
	global_load_lds_dwordx4 v[136:137], off
	s_mov_b32 m0, s7
	v_readfirstlane_b32 s7, v8
	v_add_u32_e32 v8, 0x8000, v7
	global_load_lds_dwordx4 v[138:139], off
	v_lshl_add_u64 v[4:5], v[0:1], 0, 64
	s_mov_b32 m0, s7
	v_readfirstlane_b32 s7, v8
	global_load_lds_dwordx4 v[4:5], off
	v_lshl_add_u64 v[4:5], v[2:3], 0, 64
	s_mov_b32 m0, s7
	v_lshl_add_u64 v[0:1], v[0:1], 0, s[0:1]
	global_load_lds_dwordx4 v[4:5], off
	v_add_u32_e32 v4, 0xc000, v6
	s_mov_b64 s[12:13], 0
	v_readfirstlane_b32 s7, v4
	v_add_u32_e32 v4, 0xc000, v7
	s_mov_b32 m0, s7
	v_readfirstlane_b32 s7, v4
	v_add_u32_e32 v4, s2, v209
	global_load_lds_dwordx4 v[140:141], off
	s_mov_b32 m0, s7
	v_readfirstlane_b32 s7, v4
	global_load_lds_dwordx4 v[142:143], off
	s_mov_b32 m0, s7
	v_mov_b32_e32 v4, 0
	global_load_lds_dwordx4 v[0:1], off
	v_lshl_add_u64 v[0:1], v[2:3], 0, s[0:1]
	v_add_u32_e32 v2, s2, v162
	v_mov_b32_e32 v3, v133
	v_readfirstlane_b32 s7, v2
	s_mov_b32 m0, s7
	v_mov_b32_e32 v2, v133
	global_load_lds_dwordx4 v[0:1], off
	v_add_u32_e32 v0, s4, v209
	v_mov_b32_e32 v1, v133
	v_readfirstlane_b32 s7, v0
	v_add_u32_e32 v0, s4, v162
	s_mov_b32 m0, s7
	v_readfirstlane_b32 s7, v0
	global_load_lds_dwordx4 v[144:145], off
	s_mov_b32 m0, s7
	s_mov_b32 s7, 0x18000
	global_load_lds_dwordx4 v[146:147], off
	v_mov_b32_e32 v0, 0
	v_mov_b32_e32 v5, v133
	v_mov_b32_e32 v6, v133
	v_mov_b32_e32 v7, v133
	v_mov_b32_e32 v8, 0
	v_mov_b32_e32 v9, v133
	v_mov_b32_e32 v10, v133
	v_mov_b32_e32 v11, v133
	v_mov_b32_e32 v12, 0
	v_mov_b32_e32 v13, v133
	v_mov_b32_e32 v14, v133
	v_mov_b32_e32 v15, v133
	v_mov_b32_e32 v16, 0
	v_mov_b32_e32 v17, v133
	v_mov_b32_e32 v18, v133
	v_mov_b32_e32 v19, v133
	v_mov_b32_e32 v20, 0
	v_mov_b32_e32 v21, v133
	v_mov_b32_e32 v22, v133
	v_mov_b32_e32 v23, v133
	v_mov_b32_e32 v24, 0
	v_mov_b32_e32 v25, v133
	v_mov_b32_e32 v26, v133
	v_mov_b32_e32 v27, v133
	v_mov_b32_e32 v28, 0
	v_mov_b32_e32 v29, v133
	v_mov_b32_e32 v30, v133
	v_mov_b32_e32 v31, v133
	v_mov_b32_e32 v32, 0
	v_mov_b32_e32 v33, v133
	v_mov_b32_e32 v34, v133
	v_mov_b32_e32 v35, v133
	v_mov_b32_e32 v36, 0
	v_mov_b32_e32 v37, v133
	v_mov_b32_e32 v38, v133
	v_mov_b32_e32 v39, v133
	v_mov_b32_e32 v40, 0
	v_mov_b32_e32 v41, v133
	v_mov_b32_e32 v42, v133
	v_mov_b32_e32 v43, v133
	v_mov_b32_e32 v44, 0
	v_mov_b32_e32 v45, v133
	v_mov_b32_e32 v46, v133
	v_mov_b32_e32 v47, v133
	v_mov_b32_e32 v48, 0
	v_mov_b32_e32 v49, v133
	v_mov_b32_e32 v50, v133
	v_mov_b32_e32 v51, v133
	v_mov_b32_e32 v52, 0
	v_mov_b32_e32 v53, v133
	v_mov_b32_e32 v54, v133
	v_mov_b32_e32 v55, v133
	v_mov_b32_e32 v56, 0
	v_mov_b32_e32 v57, v133
	v_mov_b32_e32 v58, v133
	v_mov_b32_e32 v59, v133
	v_mov_b32_e32 v60, 0
	v_mov_b32_e32 v61, v133
	v_mov_b32_e32 v62, v133
	v_mov_b32_e32 v63, v133
	v_mov_b32_e32 v64, 0
	v_mov_b32_e32 v65, v133
	v_mov_b32_e32 v66, v133
	v_mov_b32_e32 v67, v133
	v_mov_b32_e32 v68, 0
	v_mov_b32_e32 v69, v133
	v_mov_b32_e32 v70, v133
	v_mov_b32_e32 v71, v133
	v_mov_b32_e32 v72, 0
	v_mov_b32_e32 v73, v133
	v_mov_b32_e32 v74, v133
	v_mov_b32_e32 v75, v133
	v_mov_b32_e32 v76, 0
	v_mov_b32_e32 v77, v133
	v_mov_b32_e32 v78, v133
	v_mov_b32_e32 v79, v133
	v_mov_b32_e32 v80, 0
	v_mov_b32_e32 v81, v133
	v_mov_b32_e32 v82, v133
	v_mov_b32_e32 v83, v133
	v_mov_b32_e32 v84, 0
	v_mov_b32_e32 v85, v133
	v_mov_b32_e32 v86, v133
	v_mov_b32_e32 v87, v133
	v_mov_b32_e32 v88, 0
	v_mov_b32_e32 v89, v133
	v_mov_b32_e32 v90, v133
	v_mov_b32_e32 v91, v133
	v_mov_b32_e32 v92, 0
	v_mov_b32_e32 v93, v133
	v_mov_b32_e32 v94, v133
	v_mov_b32_e32 v95, v133
	v_mov_b32_e32 v96, 0
	v_mov_b32_e32 v97, v133
	v_mov_b32_e32 v98, v133
	v_mov_b32_e32 v99, v133
	v_mov_b32_e32 v100, 0
	v_mov_b32_e32 v101, v133
	v_mov_b32_e32 v102, v133
	v_mov_b32_e32 v103, v133
	v_mov_b32_e32 v104, 0
	v_mov_b32_e32 v105, v133
	v_mov_b32_e32 v106, v133
	v_mov_b32_e32 v107, v133
	v_mov_b32_e32 v108, 0
	v_mov_b32_e32 v109, v133
	v_mov_b32_e32 v110, v133
	v_mov_b32_e32 v111, v133
	v_mov_b32_e32 v112, 0
	v_mov_b32_e32 v113, v133
	v_mov_b32_e32 v114, v133
	v_mov_b32_e32 v115, v133
	v_mov_b32_e32 v116, 0
	v_mov_b32_e32 v117, v133
	v_mov_b32_e32 v118, v133
	v_mov_b32_e32 v119, v133
	v_mov_b32_e32 v120, 0
	v_mov_b32_e32 v121, v133
	v_mov_b32_e32 v122, v133
	v_mov_b32_e32 v123, v133
	v_mov_b32_e32 v124, 0
	v_mov_b32_e32 v125, v133
	v_mov_b32_e32 v126, v133
	v_mov_b32_e32 v127, v133
	v_readfirstlane_b32 s11, v209
	s_mov_b32 s7, 0
	s_mov_b64 s[12:13], 0
	s_cmpk_lt_u32 s11, 0x1000
	s_cbranch_scc1 .Lgemm_p8_np
	s_setprio 1
.Lgemm_p8_np:
	s_waitcnt vmcnt(8)
	s_barrier
	v_add3_u32 v187, v181, v163, s7
	v_add3_u32 v186, v181, v164, s7
	s_nop 0
	ds_read_b128 v[194:197], v187 offset:16384
	ds_read_b128 v[198:201], v187 offset:17408
	ds_read_b128 v[216:219], v187 offset:18432
	ds_read_b128 v[220:223], v187 offset:19456
	ds_read_b128 v[202:205], v186
	ds_read_b128 v[212:215], v186 offset:1024

; DI unsigned pack2bf(float a, float b) { const f2_t v = {a, b}; return __builtin_bit_cast(unsigned, __builtin_convertvector(v, bf2_t)); }
; template <class Epi>
; DI void gemm_tile256(const u16* __restrict__ Ag, long lda, const u16* __restrict__ Bg, long ldb, int nk, char* shm, Epi&& epi) {
;     ...
;   __syncthreads();
; #pragma unroll
;   for (int m = 0; m < 8; ++m)
; #pragma unroll
;     for (int n = 0; n < 4; ++n) epi(wr * 128 + m * 16 + fr, wc * 64 + n * 16 + fq * 4, acc[m][n]);
; DI void phase8(const Params& P, char* smem) {
;     ...
;     gemm_tile256(h1b + (long)brow * 1024, 1024, WqT + (long)bcol * 1024, 1024, 32, smem, [&](int row, int col0, f32x4 v) {
;       *reinterpret_cast<uint2*>(Qp + (long)(brow + row) * 2048 + bcol + col0) = make_uint2(pack2bf(v[0], v[1]), pack2bf(v[2], v[3]));
;     });
.Lgemm_p8_kend:
	s_setprio 0
	s_nop 7
	s_nop 3
	s_waitcnt vmcnt(0) lgkmcnt(0)
	s_barrier
	v_and_b32_e32 v186, 15, v208
	v_lshrrev_b32_e32 v187, 4, v208
	v_lshrrev_b32_e32 v206, 6, v189
	v_lshlrev_b32_e32 v206, 14, v206
	v_and_b32_e32 v207, 7, v186
	v_lshrrev_b32_e32 v224, 1, v187
	v_and_b32_e32 v225, 1, v187
	v_lshl_add_u32 v226, v186, 7, v206
	v_lshl_add_u32 v226, v225, 3, v226
	v_or_b32_e32 v227, 0, v224
	v_xor_b32_e32 v227, v227, v207
	v_lshl_add_u32 v232, v227, 4, v226
	v_or_b32_e32 v227, 2, v224
	v_xor_b32_e32 v227, v227, v207
	v_lshl_add_u32 v233, v227, 4, v226
	v_or_b32_e32 v227, 4, v224
	v_xor_b32_e32 v227, v227, v207
	v_lshl_add_u32 v234, v227, 4, v226
	v_or_b32_e32 v227, 6, v224
	v_xor_b32_e32 v227, v227, v207
	v_lshl_add_u32 v235, v227, 4, v226
	v_lshrrev_b32_e32 v228, 3, v208
	v_and_b32_e32 v229, 7, v208
	v_xor_b32_e32 v227, v229, v228
	v_lshl_add_u32 v236, v228, 7, v206
	v_lshl_add_u32 v236, v227, 4, v236
	v_lshl_add_u32 v227, v190, 7, v228
	v_add_u32_e32 v227, s10, v227
	v_lshlrev_b32_e32 v238, 12, v227
	v_bfe_u32 v227, v189, 6, 2
	v_lshl_add_u32 v238, v227, 7, v238
	v_lshl_add_u32 v238, v229, 4, v238
	v_mov_b32_e32 v239, 0
	s_and_b32 s26, s74, 7
	s_lshl_b32 s26, s26, 9
	s_add_u32 s26, s26, 0x8000000
	s_add_u32 s26, s78, s26
	s_addc_u32 s27, s79, 0
	v_lshl_add_u64 v[238:239], v[238:239], 0, s[26:27]
	s_mov_b32 s28, 0x8000
	s_mov_b32 s29, 0
	v_lshl_add_u64 v[240:241], v[238:239], 0, s[28:29]
	s_lshl_b32 s28, s28, 1
	v_cvt_pk_bf16_f32 v124, v124, v125
	v_cvt_pk_bf16_f32 v125, v126, v127
	ds_write_b64 v232, v[124:125] offset:0
	v_cvt_pk_bf16_f32 v120, v120, v121
	v_cvt_pk_bf16_f32 v121, v122, v123
	ds_write_b64 v233, v[120:121] offset:0
	v_cvt_pk_bf16_f32 v116, v116, v117
	v_cvt_pk_bf16_f32 v117, v118, v119
	ds_write_b64 v234, v[116:117] offset:0
	v_cvt_pk_bf16_f32 v112, v112, v113
	v_cvt_pk_bf16_f32 v113, v114, v115
	ds_write_b64 v235, v[112:113] offset:0
	v_cvt_pk_bf16_f32 v108, v108, v109
	v_cvt_pk_bf16_f32 v109, v110, v111
	ds_write_b64 v232, v[108:109] offset:2048
	v_cvt_pk_bf16_f32 v104, v104, v105
	v_cvt_pk_bf16_f32 v105, v106, v107
	ds_write_b64 v233, v[104:105] offset:2048
	v_cvt_pk_bf16_f32 v100, v100, v101
	v_cvt_pk_bf16_f32 v101, v102, v103
	ds_write_b64 v234, v[100:101] offset:2048
	v_cvt_pk_bf16_f32 v96, v96, v97
	v_cvt_pk_bf16_f32 v97, v98, v99
	ds_write_b64 v235, v[96:97] offset:2048
	v_cvt_pk_bf16_f32 v92, v92, v93
	v_cvt_pk_bf16_f32 v93, v94, v95
	ds_write_b64 v232, v[92:93] offset:4096
	v_cvt_pk_bf16_f32 v88, v88, v89
	v_cvt_pk_bf16_f32 v89, v90, v91
	ds_write_b64 v233, v[88:89] offset:4096
	v_cvt_pk_bf16_f32 v84, v84, v85
	v_cvt_pk_bf16_f32 v85, v86, v87
	ds_write_b64 v234, v[84:85] offset:4096
	v_cvt_pk_bf16_f32 v80, v80, v81
	v_cvt_pk_bf16_f32 v81, v82, v83
	ds_write_b64 v235, v[80:81] offset:4096
	v_cvt_pk_bf16_f32 v76, v76, v77
	v_cvt_pk_bf16_f32 v77, v78, v79
	ds_write_b64 v232, v[76:77] offset:6144
	v_cvt_pk_bf16_f32 v72, v72, v73
	v_cvt_pk_bf16_f32 v73, v74, v75
	ds_write_b64 v233, v[72:73] offset:6144
	v_cvt_pk_bf16_f32 v68, v68, v69
	v_cvt_pk_bf16_f32 v69, v70, v71
	ds_write_b64 v234, v[68:69] offset:6144
	v_cvt_pk_bf16_f32 v64, v64, v65
	v_cvt_pk_bf16_f32 v65, v66, v67
	ds_write_b64 v235, v[64:65] offset:6144
	v_cvt_pk_bf16_f32 v60, v60, v61
	v_cvt_pk_bf16_f32 v61, v62, v63
	ds_write_b64 v232, v[60:61] offset:8192
	v_cvt_pk_bf16_f32 v56, v56, v57
	v_cvt_pk_bf16_f32 v57, v58, v59
	ds_write_b64 v233, v[56:57] offset:8192
	v_cvt_pk_bf16_f32 v52, v52, v53
	v_cvt_pk_bf16_f32 v53, v54, v55
	ds_write_b64 v234, v[52:53] offset:8192
	v_cvt_pk_bf16_f32 v48, v48, v49
	v_cvt_pk_bf16_f32 v49, v50, v51
	ds_write_b64 v235, v[48:49] offset:8192
	v_cvt_pk_bf16_f32 v44, v44, v45
	v_cvt_pk_bf16_f32 v45, v46, v47
	ds_write_b64 v232, v[44:45] offset:10240
	v_cvt_pk_bf16_f32 v40, v40, v41
	v_cvt_pk_bf16_f32 v41, v42, v43
	ds_write_b64 v233, v[40:41] offset:10240
	v_cvt_pk_bf16_f32 v36, v36, v37
	v_cvt_pk_bf16_f32 v37, v38, v39
	ds_write_b64 v234, v[36:37] offset:10240
	v_cvt_pk_bf16_f32 v32, v32, v33
	v_cvt_pk_bf16_f32 v33, v34, v35
	ds_write_b64 v235, v[32:33] offset:10240
	v_cvt_pk_bf16_f32 v28, v28, v29
	v_cvt_pk_bf16_f32 v29, v30, v31
	ds_write_b64 v232, v[28:29] offset:12288
	v_cvt_pk_bf16_f32 v24, v24, v25
	v_cvt_pk_bf16_f32 v25, v26, v27
	ds_write_b64 v233, v[24:25] offset:12288
	v_cvt_pk_bf16_f32 v20, v20, v21
	v_cvt_pk_bf16_f32 v21, v22, v23
	ds_write_b64 v234, v[20:21] offset:12288
	v_cvt_pk_bf16_f32 v16, v16, v17
	v_cvt_pk_bf16_f32 v17, v18, v19
	ds_write_b64 v235, v[16:17] offset:12288
	v_cvt_pk_bf16_f32 v12, v12, v13
	v_cvt_pk_bf16_f32 v13, v14, v15
	ds_write_b64 v232, v[12:13] offset:14336
	v_cvt_pk_bf16_f32 v8, v8, v9
	v_cvt_pk_bf16_f32 v9, v10, v11
	ds_write_b64 v233, v[8:9] offset:14336
	v_cvt_pk_bf16_f32 v4, v4, v5
	v_cvt_pk_bf16_f32 v5, v6, v7
	ds_write_b64 v234, v[4:5] offset:14336
	v_cvt_pk_bf16_f32 v0, v0, v1
	v_cvt_pk_bf16_f32 v1, v2, v3
	ds_write_b64 v235, v[0:1] offset:14336
	s_waitcnt lgkmcnt(0)
; DI unsigned pack2bf(float a, float b) { const f2_t v = {a, b}; return __builtin_bit_cast(unsigned, __builtin_convertvector(v, bf2_t)); }
; DI void phase8(const Params& P, char* smem) {
;     ...
;   for (int q = RBLK >> 3; q < 128; q += RGRID >> 3) {
;     const int brow = q * 256, bcol = (RBLK & 7) * 256;
;     gemm_tile256(h1b + (long)brow * 1024, 1024, WqT + (long)bcol * 1024, 1024, 32, smem, [&](int row, int col0, f32x4 v) {
;       *reinterpret_cast<uint2*>(Qp + (long)(brow + row) * 2048 + bcol + col0) = make_uint2(pack2bf(v[0], v[1]), pack2bf(v[2], v[3]));
;     });
	ds_read_b128 v[194:197], v236 offset:0
	ds_read_b128 v[198:201], v236 offset:1024
	ds_read_b128 v[202:205], v236 offset:2048
	ds_read_b128 v[212:215], v236 offset:3072
	s_waitcnt lgkmcnt(3)
	global_store_dwordx4 v[238:239], v[194:197], off
	s_nop 0
	v_lshl_add_u64 v[238:239], v[238:239], 0, s[28:29]
	s_waitcnt lgkmcnt(2)
	global_store_dwordx4 v[240:241], v[198:201], off
	s_nop 0
	v_lshl_add_u64 v[240:241], v[240:241], 0, s[28:29]
	s_waitcnt lgkmcnt(1)
	global_store_dwordx4 v[238:239], v[202:205], off
	s_nop 0
	v_lshl_add_u64 v[238:239], v[238:239], 0, s[28:29]
	s_waitcnt lgkmcnt(0)
	global_store_dwordx4 v[240:241], v[212:215], off
	s_nop 0
	v_lshl_add_u64 v[240:241], v[240:241], 0, s[28:29]
	ds_read_b128 v[216:219], v236 offset:4096
	ds_read_b128 v[220:223], v236 offset:5120
	ds_read_b128 v[244:247], v236 offset:6144
	ds_read_b128 v[248:251], v236 offset:7168
	s_waitcnt lgkmcnt(3)
	global_store_dwordx4 v[238:239], v[216:219], off
	s_nop 0
	v_lshl_add_u64 v[238:239], v[238:239], 0, s[28:29]
	s_waitcnt lgkmcnt(2)
	global_store_dwordx4 v[240:241], v[220:223], off
	s_nop 0
	v_lshl_add_u64 v[240:241], v[240:241], 0, s[28:29]
	s_waitcnt lgkmcnt(1)
	global_store_dwordx4 v[238:239], v[244:247], off
	s_nop 0
	v_lshl_add_u64 v[238:239], v[238:239], 0, s[28:29]
	s_waitcnt lgkmcnt(0)
	global_store_dwordx4 v[240:241], v[248:251], off
	s_nop 0
	v_lshl_add_u64 v[240:241], v[240:241], 0, s[28:29]
	ds_read_b128 v[194:197], v236 offset:8192
	ds_read_b128 v[198:201], v236 offset:9216
	ds_read_b128 v[202:205], v236 offset:10240
	ds_read_b128 v[212:215], v236 offset:11264
	s_waitcnt lgkmcnt(3)
	global_store_dwordx4 v[238:239], v[194:197], off
	s_nop 0
	v_lshl_add_u64 v[238:239], v[238:239], 0, s[28:29]
	s_waitcnt lgkmcnt(2)
	global_store_dwordx4 v[240:241], v[198:201], off
	s_nop 0
	v_lshl_add_u64 v[240:241], v[240:241], 0, s[28:29]
	s_waitcnt lgkmcnt(1)
	global_store_dwordx4 v[238:239], v[202:205], off
	s_nop 0
	v_lshl_add_u64 v[238:239], v[238:239], 0, s[28:29]
	s_waitcnt lgkmcnt(0)
	global_store_dwordx4 v[240:241], v[212:215], off
	s_nop 0
	v_lshl_add_u64 v[240:241], v[240:241], 0, s[28:29]
	ds_read_b128 v[216:219], v236 offset:12288
	ds_read_b128 v[220:223], v236 offset:13312
	ds_read_b128 v[244:247], v236 offset:14336
	ds_read_b128 v[248:251], v236 offset:15360
	s_waitcnt lgkmcnt(3)
	global_store_dwordx4 v[238:239], v[216:219], off
	s_nop 0
	v_lshl_add_u64 v[238:239], v[238:239], 0, s[28:29]
	s_waitcnt lgkmcnt(2)
	global_store_dwordx4 v[240:241], v[220:223], off
	s_nop 0
	v_lshl_add_u64 v[240:241], v[240:241], 0, s[28:29]
	s_waitcnt lgkmcnt(1)
	global_store_dwordx4 v[238:239], v[244:247], off
	s_nop 0
	v_lshl_add_u64 v[238:239], v[238:239], 0, s[28:29]
	s_waitcnt lgkmcnt(0)
	global_store_dwordx4 v[240:241], v[248:251], off
	s_nop 0
	v_lshl_add_u64 v[240:241], v[240:241], 0, s[28:29]
	s_add_i32 s75, s75, s5
	s_add_i32 s6, s6, s8
	s_cmpk_lt_i32 s75, 0x80
	s_cbranch_scc1 .LBB0_1068
